# speedup vs baseline: 1.0053x; 1.0053x over previous
; __device__ __forceinline__ int opaque_tid() { int t = threadIdx.x; asm volatile("" : "+v"(t)); return t; }
; template <int AMODE>
; __device__ __forceinline__ void gemm_kloop(f32x4 (&acc)[4][4], const u16* __restrict__ A, int lda,
;                                            const u16* __restrict__ Bt, int ldb, int K, char* smem,
;                                            const float* __restrict__ ssq_rows) {
;     const int tid = opaque_tid(), lane = tid & 63, wid = tid >> 6, wr = wid >> 1, wc = wid & 1;
;     const int r = lane & 15, g4 = lane >> 4;
;     char* As = smem; char* Bs = smem + 32768;
;     const int grow = wid * 8 + (lane >> 3);
;     const int gch = ((lane & 7) ^ ((lane >> 3) & 7)) * 8;
;     const u16* Ag = A + (size_t)grow * lda + gch;
;     const u16* Bg = Bt + (size_t)grow * ldb + gch;
;     const int lrow = tid >> 3, lkc = tid & 7;
;     const u16* Ap = A + (size_t)lrow * lda + lkc * 8;
;     const int lds_w = lrow * 128 + ((lkc ^ (lrow & 7)) << 4);
;     uint4 ra[4];
;     float rs[4];
;     const int nk = K >> 6;
;     ...
;     GLOAD(0, 0);
;     LSTORE(0);
;     asm volatile("s_waitcnt vmcnt(0)" ::: "memory");
;     __syncthreads();
; __device__ void phaseC1(const Params& p, int l, char* smem) {
;     ...
;     for (int k = 0; k < 5; ++k) {
;         int mt, nt;
;         if (!tile_map(k, 8, mt, nt)) continue;
;         const int m0 = mt * 128, n0 = nt * 128;
;         f32x4 acc[4][4];
; #pragma unroll
;         for (int i = 0; i < 4; ++i)
; #pragma unroll
;             for (int j = 0; j < 4; ++j) acc[i][j] = (f32x4){0.f, 0.f, 0.f, 0.f};
;         gemm_kloop<0>(acc, p.ygb + (size_t)m0 * 2048, 2048, p.wt_m + ((size_t)l * 1024 + n0) * 2048, 2048, 2048, smem, nullptr);
.LBB0_706:
	s_lshl_b32 s8, s15, 7
	s_ashr_i32 s9, s8, 31
	v_readlane_b32 s36, v214, 34
	s_lshl_b32 s6, s16, 7
	s_lshl_b64 s[12:13], s[8:9], 12
	v_readlane_b32 s46, v214, 44
	v_readlane_b32 s47, v214, 45
	s_add_u32 s18, s46, s12
	s_addc_u32 s19, s47, s13
	s_ashr_i32 s7, s6, 31
	s_add_u32 s10, s6, s2
	v_mov_b32_e32 v10, v141
	s_addc_u32 s11, s7, 0
	s_lshl_b64 s[20:21], s[10:11], 12
	v_ashrrev_i32_e32 v8, 6, v10
	v_bfe_u32 v0, v10, 3, 3
	v_lshl_or_b32 v2, v8, 3, v0
	v_readlane_b32 s37, v214, 35
	s_add_u32 s20, s36, s20
	v_ashrrev_i32_e32 v3, 31, v2
	v_lshlrev_b32_e32 v70, 10, v8
	s_addc_u32 s21, s37, s21
	v_bitop3_b32 v0, v0, v10, 7 bitop3:0x78
	v_lshlrev_b64 v[2:3], 12, v[2:3]
	v_add_u32_e32 v8, 0x8000, v70
	v_lshlrev_b32_e32 v0, 4, v0
	v_lshl_add_u64 v[6:7], s[20:21], 0, v[2:3]
	v_readfirstlane_b32 s17, v8
	v_lshl_add_u64 v[4:5], s[18:19], 0, v[2:3]
	v_lshl_add_u64 v[6:7], v[6:7], 0, v[0:1]
	s_mov_b32 m0, s17
	v_readfirstlane_b32 s17, v70
	v_add_u32_e32 v12, 0x9000, v70
	v_lshl_add_u64 v[4:5], v[4:5], 0, v[0:1]
	global_load_lds_dwordx4 v[6:7], off
	s_mov_b32 m0, s17
	s_mov_b64 s[18:19], 0x20000
	v_readfirstlane_b32 s17, v12
	v_add_u32_e32 v12, 0x1000, v70
	global_load_lds_dwordx4 v[4:5], off
	v_lshl_add_u64 v[8:9], v[6:7], 0, s[18:19]
	s_mov_b32 m0, s17
	v_readfirstlane_b32 s17, v12
	v_add_u32_e32 v12, 0xa000, v70
	global_load_lds_dwordx4 v[8:9], off
	v_lshl_add_u64 v[8:9], v[4:5], 0, s[18:19]
	s_mov_b32 m0, s17
	s_mov_b64 s[18:19], 0x40000
	v_readfirstlane_b32 s17, v12
	v_add_u32_e32 v12, 0x2000, v70
	global_load_lds_dwordx4 v[8:9], off
	v_lshl_add_u64 v[8:9], v[6:7], 0, s[18:19]
	s_mov_b32 m0, s17
	v_readfirstlane_b32 s17, v12
	global_load_lds_dwordx4 v[8:9], off
	v_lshl_add_u64 v[8:9], v[4:5], 0, s[18:19]
	s_mov_b32 m0, s17
	s_mov_b64 s[18:19], 0x60000
	global_load_lds_dwordx4 v[8:9], off
	v_add_u32_e32 v8, 0xb000, v70
	v_lshl_add_u64 v[6:7], v[6:7], 0, s[18:19]
	v_readfirstlane_b32 s17, v8
	s_mov_b32 m0, s17
	v_lshl_add_u64 v[4:5], v[4:5], 0, s[18:19]
	global_load_lds_dwordx4 v[6:7], off
	v_add_u32_e32 v6, 0x3000, v70
	v_and_b32_e32 v11, 7, v10
	v_readfirstlane_b32 s17, v6
	s_mov_b32 m0, s17
	v_lshrrev_b32_e32 v6, 1, v10
	global_load_lds_dwordx4 v[4:5], off
	v_and_b32_e32 v5, 15, v10
	s_mov_b32 s17, 0x1ffffc0
	v_and_or_b32 v5, v6, s17, v5
	v_bfe_u32 v4, v10, 4, 2
	v_lshlrev_b32_e32 v72, 7, v5
	v_lshlrev_b32_e32 v5, 7, v10
	v_and_b32_e32 v71, 0x2780, v5
	v_bitop3_b32 v5, v4, v10, 7 bitop3:0x78
	v_bitop3_b32 v4, v4, v11, 4 bitop3:0x36
	s_lshl_b64 s[18:19], s[6:7], 12
	v_lshlrev_b32_e32 v74, 4, v5
	v_lshlrev_b32_e32 v73, 4, v4
	v_lshl_add_u64 v[4:5], s[18:19], 0, v[2:3]
	v_lshl_add_u64 v[2:3], s[12:13], 0, v[2:3]
	s_waitcnt vmcnt(0)
	v_or_b32_e32 v2, v2, v0
	v_or_b32_e32 v4, v4, v0
	v_lshl_add_u64 v[68:69], s[46:47], 0, v[2:3]
	v_mov_b32_e32 v2, 0
	v_lshl_add_u64 v[66:67], s[0:1], 0, v[4:5]
	s_mov_b64 s[12:13], 0
	s_mov_b32 s17, 0
	v_mov_b32_e32 v3, v2
	v_mov_b32_e32 v4, v2
	v_mov_b32_e32 v5, v2
	v_mov_b32_e32 v6, v2
	v_mov_b32_e32 v7, v2
	v_mov_b32_e32 v8, v2
	v_mov_b32_e32 v9, v2
	v_mov_b32_e32 v10, v2
	v_mov_b32_e32 v11, v2
	v_mov_b32_e32 v12, v2
	v_mov_b32_e32 v13, v2
	v_mov_b32_e32 v14, v2
	v_mov_b32_e32 v15, v2
	v_mov_b32_e32 v16, v2
	v_mov_b32_e32 v17, v2
	v_mov_b32_e32 v18, v2
	v_mov_b32_e32 v19, v2
	v_mov_b32_e32 v20, v2
	v_mov_b32_e32 v21, v2
	v_mov_b32_e32 v22, v2
	v_mov_b32_e32 v23, v2
	v_mov_b32_e32 v24, v2
	v_mov_b32_e32 v25, v2
	v_mov_b32_e32 v26, v2
	v_mov_b32_e32 v27, v2
	v_mov_b32_e32 v28, v2
	v_mov_b32_e32 v29, v2
	v_mov_b32_e32 v30, v2
	v_mov_b32_e32 v31, v2
	v_mov_b32_e32 v32, v2
	v_mov_b32_e32 v33, v2
	v_mov_b32_e32 v34, v2
	v_mov_b32_e32 v35, v2
	v_mov_b32_e32 v36, v2
	v_mov_b32_e32 v37, v2
	v_mov_b32_e32 v38, v2
	v_mov_b32_e32 v39, v2
	v_mov_b32_e32 v40, v2
	v_mov_b32_e32 v41, v2
	v_mov_b32_e32 v42, v2
	v_mov_b32_e32 v43, v2
	v_mov_b32_e32 v44, v2
	v_mov_b32_e32 v45, v2
	v_mov_b32_e32 v46, v2
	v_mov_b32_e32 v47, v2
	v_mov_b32_e32 v48, v2
	v_mov_b32_e32 v49, v2
	v_mov_b32_e32 v50, v2
	v_mov_b32_e32 v51, v2
	v_mov_b32_e32 v52, v2
	v_mov_b32_e32 v53, v2
	v_mov_b32_e32 v54, v2
	v_mov_b32_e32 v55, v2
	v_mov_b32_e32 v56, v2
	v_mov_b32_e32 v57, v2
	v_mov_b32_e32 v58, v2
	v_mov_b32_e32 v59, v2
	v_mov_b32_e32 v60, v2
	v_mov_b32_e32 v61, v2
	v_mov_b32_e32 v62, v2
	v_mov_b32_e32 v63, v2
	v_mov_b32_e32 v64, v2
	v_mov_b32_e32 v65, v2
	s_mov_b64 s[20:21], 0x40080
	s_mov_b64 s[22:23], 0x60080
	v_readlane_b32 s38, v214, 36
	v_readlane_b32 s39, v214, 37
	v_readlane_b32 s40, v214, 38
	v_readlane_b32 s41, v214, 39
	v_readlane_b32 s42, v214, 40
	v_readlane_b32 s43, v214, 41
	v_readlane_b32 s44, v214, 42
	v_readlane_b32 s45, v214, 43
	v_readlane_b32 s48, v214, 46
	v_readlane_b32 s49, v214, 47
	v_readlane_b32 s50, v214, 48
	v_readlane_b32 s51, v214, 49
	s_waitcnt vmcnt(0) lgkmcnt(0)
	s_barrier
	v_lshrrev_b32_e32 v220, 6, v141
	v_bfe_u32 v221, v141, 3, 3
	v_lshl_or_b32 v216, v220, 3, v221
	v_and_b32_e32 v222, 7, v141
	v_xor_b32_e32 v222, v222, v221
	v_lshlrev_b32_e32 v222, 4, v222
	v_lshl_or_b32 v216, v216, 12, v222
	v_add_u32_e32 v217, 0x20000, v216
	v_add_u32_e32 v218, 0x40000, v216
	v_add_u32_e32 v219, 0x60000, v216
	v_readfirstlane_b32 s19, v220
	s_lshl_b32 s19, s19, 15
	v_readfirstlane_b32 s100, v66
	v_readfirstlane_b32 s101, v67
	s_sub_u32 s100, s100, s19
	s_subb_u32 s101, s101, 0
	v_readfirstlane_b32 s98, v68
	v_readfirstlane_b32 s99, v69
	s_sub_u32 s98, s98, s19
	s_subb_u32 s99, s99, 0
; #define MFMA(a, b, c) __builtin_amdgcn_mfma_f32_16x16x32_bf16((a), (b), (c), 0, 0, 0)
; template <int AMODE>
; __device__ __forceinline__ void gemm_kloop(f32x4 (&acc)[4][4], const u16* __restrict__ A, int lda,
;                                            const u16* __restrict__ Bt, int ldb, int K, char* smem,
;                                            const float* __restrict__ ssq_rows) {
;     ...
;     for (int kt = 0; kt < nk; ++kt) {
;         const int buf = kt & 1;
;         if (kt + 1 < nk) GLOAD(kt + 1, buf ^ 1);
;         const char* ab = As + buf * 16384 + (wr * 64 + r) * 128;
;         const char* bb = Bs + buf * 16384 + (wc * 64 + r) * 128;
;         bf16x8 af[2][4], bfr[2][4];
; #pragma unroll
;         for (int ks = 0; ks < 2; ++ks) {
;             const int co = ((ks * 4 + g4) ^ (r & 7)) << 4;
; #pragma unroll
;             for (int i = 0; i < 4; ++i) af[ks][i] = ld_frag(ab + i * 2048 + co);
; #pragma unroll
;             for (int j = 0; j < 4; ++j) bfr[ks][j] = ld_frag(bb + j * 2048 + co);
;         }
;         __builtin_amdgcn_sched_barrier(0);
;         __builtin_amdgcn_s_setprio(1);
; #pragma unroll
;         for (int ks = 0; ks < 2; ++ks)
; #pragma unroll
;             for (int i = 0; i < 4; ++i)
; #pragma unroll
;                 for (int j = 0; j < 4; ++j) acc[i][j] = MFMA(bfr[ks][j], af[ks][i], acc[i][j]);
;         __builtin_amdgcn_s_setprio(0);
;         __builtin_amdgcn_sched_barrier(0);
;         if (kt + 1 < nk) LSTORE(buf ^ 1);
;         asm volatile("s_waitcnt vmcnt(0)" ::: "memory");
;         __syncthreads();
;     }
.LBB0_707:
	s_setprio 1
	s_and_b32 s18, s17, 0x4000
	s_xor_b32 s19, s18, 0x4000
	v_add_u32_e32 v0, s19, v70
	s_add_u32 s100, s100, 0x80
	s_addc_u32 s101, s101, 0
	s_add_u32 s98, s98, 0x80
	s_addc_u32 s99, s99, 0
	v_readfirstlane_b32 s19, v0
	s_add_u32 m0, s19, 0x8000
	v_add_u32_e32 v0, s18, v72
	global_load_lds_dwordx4 v216, s[100:101]
	v_or_b32_e32 v75, s18, v71
	s_add_u32 m0, s19, 0x0
	v_add_u32_e32 v90, v0, v74
	global_load_lds_dwordx4 v216, s[98:99]
	v_add_u32_e32 v102, v75, v74
	s_add_u32 m0, s19, 0x9000
	v_add_u32_e32 v0, v0, v73
	global_load_lds_dwordx4 v217, s[100:101]
	ds_read_b128 v[76:79], v90
	s_add_u32 m0, s19, 0x1000
	ds_read_b128 v[80:83], v90 offset:2048
	global_load_lds_dwordx4 v217, s[98:99]
	ds_read_b128 v[84:87], v90 offset:4096
	s_add_u32 m0, s19, 0xa000
	ds_read_b128 v[90:93], v90 offset:6144
	global_load_lds_dwordx4 v218, s[100:101]
	ds_read_b128 v[94:97], v102 offset:32768
	s_add_u32 m0, s19, 0x2000
	ds_read_b128 v[98:101], v102 offset:34816
	global_load_lds_dwordx4 v218, s[98:99]
	ds_read_b128 v[110:113], v102 offset:36864
	s_add_u32 m0, s19, 0xb000
	ds_read_b128 v[114:117], v102 offset:38912
	global_load_lds_dwordx4 v219, s[100:101]
	ds_read_b128 v[118:121], v0
	s_add_u32 m0, s19, 0x3000
	ds_read_b128 v[122:125], v0 offset:2048
	global_load_lds_dwordx4 v219, s[98:99]
	ds_read_b128 v[126:129], v0 offset:4096
	ds_read_b128 v[130:133], v0 offset:6144
	v_add_u32_e32 v0, v75, v73
	ds_read_b128 v[134:137], v0 offset:32768
	ds_read_b128 v[142:145], v0 offset:34816
	ds_read_b128 v[146:149], v0 offset:36864
	ds_read_b128 v[150:153], v0 offset:38912
	s_setprio 0
	s_waitcnt lgkmcnt(0)
	v_mfma_f32_16x16x32_bf16 v[62:65], v[94:97], v[76:79], v[62:65]
	v_mfma_f32_16x16x32_bf16 v[58:61], v[98:101], v[76:79], v[58:61]
	v_mfma_f32_16x16x32_bf16 v[54:57], v[110:113], v[76:79], v[54:57]
	v_mfma_f32_16x16x32_bf16 v[50:53], v[114:117], v[76:79], v[50:53]
	v_mfma_f32_16x16x32_bf16 v[46:49], v[94:97], v[80:83], v[46:49]
	v_mfma_f32_16x16x32_bf16 v[42:45], v[98:101], v[80:83], v[42:45]
	v_mfma_f32_16x16x32_bf16 v[38:41], v[110:113], v[80:83], v[38:41]
	v_mfma_f32_16x16x32_bf16 v[34:37], v[114:117], v[80:83], v[34:37]
	v_mfma_f32_16x16x32_bf16 v[30:33], v[94:97], v[84:87], v[30:33]
	v_mfma_f32_16x16x32_bf16 v[26:29], v[98:101], v[84:87], v[26:29]
	v_mfma_f32_16x16x32_bf16 v[22:25], v[110:113], v[84:87], v[22:25]
	v_mfma_f32_16x16x32_bf16 v[18:21], v[114:117], v[84:87], v[18:21]
	v_mfma_f32_16x16x32_bf16 v[14:17], v[94:97], v[90:93], v[14:17]
	v_mfma_f32_16x16x32_bf16 v[10:13], v[98:101], v[90:93], v[10:13]
	v_mfma_f32_16x16x32_bf16 v[6:9], v[110:113], v[90:93], v[6:9]
	v_mfma_f32_16x16x32_bf16 v[2:5], v[114:117], v[90:93], v[2:5]
	v_mfma_f32_16x16x32_bf16 v[62:65], v[134:137], v[118:121], v[62:65]
	v_mfma_f32_16x16x32_bf16 v[58:61], v[142:145], v[118:121], v[58:61]
	v_mfma_f32_16x16x32_bf16 v[54:57], v[146:149], v[118:121], v[54:57]
	v_mfma_f32_16x16x32_bf16 v[50:53], v[150:153], v[118:121], v[50:53]
	v_mfma_f32_16x16x32_bf16 v[46:49], v[134:137], v[122:125], v[46:49]
	v_mfma_f32_16x16x32_bf16 v[42:45], v[142:145], v[122:125], v[42:45]
	v_mfma_f32_16x16x32_bf16 v[38:41], v[146:149], v[122:125], v[38:41]
	v_mfma_f32_16x16x32_bf16 v[34:37], v[150:153], v[122:125], v[34:37]
	v_mfma_f32_16x16x32_bf16 v[30:33], v[134:137], v[126:129], v[30:33]
	v_mfma_f32_16x16x32_bf16 v[26:29], v[142:145], v[126:129], v[26:29]
	v_mfma_f32_16x16x32_bf16 v[22:25], v[146:149], v[126:129], v[22:25]
	v_mfma_f32_16x16x32_bf16 v[18:21], v[150:153], v[126:129], v[18:21]
	v_mfma_f32_16x16x32_bf16 v[14:17], v[134:137], v[130:133], v[14:17]
	v_mfma_f32_16x16x32_bf16 v[10:13], v[142:145], v[130:133], v[10:13]
	v_mfma_f32_16x16x32_bf16 v[6:9], v[146:149], v[130:133], v[6:9]
	v_mfma_f32_16x16x32_bf16 v[2:5], v[150:153], v[130:133], v[2:5]
	s_nop 0
	s_waitcnt vmcnt(0)
	s_add_u32 s12, s12, 0x80
	s_addc_u32 s13, s13, 0
	s_addk_i32 s17, 0x4000
	s_cmpk_eq_i32 s12, 0xf80
	s_waitcnt vmcnt(0)
	s_barrier
	s_cbranch_scc0 .LBB0_707
	v_add_u32_e32 v0, v72, v74
	ds_read_b128 v[66:69], v0 offset:16384
	ds_read_b128 v[76:79], v0 offset:18432
	ds_read_b128 v[80:83], v0 offset:20480
	ds_read_b128 v[84:87], v0 offset:22528
	v_add_u32_e32 v0, v71, v74
	ds_read_b128 v[90:93], v0 offset:49152
	ds_read_b128 v[94:97], v0 offset:51200
	ds_read_b128 v[98:101], v0 offset:53248
	ds_read_b128 v[110:113], v0 offset:55296
	v_add_u32_e32 v0, v72, v73
	ds_read_b128 v[114:117], v0 offset:16384
	ds_read_b128 v[118:121], v0 offset:18432
	ds_read_b128 v[122:125], v0 offset:20480
	ds_read_b128 v[126:129], v0 offset:22528
	v_add_u32_e32 v0, v71, v73
	ds_read_b128 v[70:73], v0 offset:49152
	ds_read_b128 v[130:133], v0 offset:51200
	ds_read_b128 v[134:137], v0 offset:53248
	ds_read_b128 v[142:145], v0 offset:55296
	s_setprio 1
	s_waitcnt lgkmcnt(11)
	v_mfma_f32_16x16x32_bf16 v[62:65], v[90:93], v[66:69], v[62:65]
	s_waitcnt lgkmcnt(10)
	v_mfma_f32_16x16x32_bf16 v[58:61], v[94:97], v[66:69], v[58:61]
	s_waitcnt lgkmcnt(9)
	v_mfma_f32_16x16x32_bf16 v[54:57], v[98:101], v[66:69], v[54:57]
	s_waitcnt lgkmcnt(8)
	v_mfma_f32_16x16x32_bf16 v[50:53], v[110:113], v[66:69], v[50:53]
	v_mfma_f32_16x16x32_bf16 v[46:49], v[90:93], v[76:79], v[46:49]
	v_mfma_f32_16x16x32_bf16 v[42:45], v[94:97], v[76:79], v[42:45]
	v_mfma_f32_16x16x32_bf16 v[38:41], v[98:101], v[76:79], v[38:41]
	v_mfma_f32_16x16x32_bf16 v[34:37], v[110:113], v[76:79], v[34:37]
	v_mfma_f32_16x16x32_bf16 v[66:69], v[90:93], v[80:83], v[30:33]
	v_mfma_f32_16x16x32_bf16 v[26:29], v[94:97], v[80:83], v[26:29]
	v_mfma_f32_16x16x32_bf16 v[74:77], v[98:101], v[80:83], v[22:25]
	v_mfma_f32_16x16x32_bf16 v[78:81], v[110:113], v[80:83], v[18:21]
	v_mfma_f32_16x16x32_bf16 v[90:93], v[90:93], v[84:87], v[14:17]
	v_mfma_f32_16x16x32_bf16 v[10:13], v[94:97], v[84:87], v[10:13]
	v_mfma_f32_16x16x32_bf16 v[6:9], v[98:101], v[84:87], v[6:9]
	v_mfma_f32_16x16x32_bf16 v[2:5], v[110:113], v[84:87], v[2:5]
	s_waitcnt lgkmcnt(3)
; __device__ __forceinline__ float bf_lo(unsigned u) { return __uint_as_float(u << 16); }
; __device__ __forceinline__ float bf_hi(unsigned u) { return __uint_as_float(u & 0xffff0000u); }
; __device__ __forceinline__ float frcp(float x) { return __builtin_amdgcn_rcpf(x); }
; #define MFMA(a, b, c) __builtin_amdgcn_mfma_f32_16x16x32_bf16((a), (b), (c), 0, 0, 0)
; template <int AMODE>
; __device__ __forceinline__ void gemm_kloop(f32x4 (&acc)[4][4], const u16* __restrict__ A, int lda,
;                                            const u16* __restrict__ Bt, int ldb, int K, char* smem,
;                                            const float* __restrict__ ssq_rows) {
;     ...
;         for (int ks = 0; ks < 2; ++ks)
; #pragma unroll
;             for (int i = 0; i < 4; ++i)
; #pragma unroll
;                 for (int j = 0; j < 4; ++j) acc[i][j] = MFMA(bfr[ks][j], af[ks][i], acc[i][j]);
; __device__ void phaseC1(const Params& p, int l, char* smem) {
;     ...
; #pragma unroll
;         for (int i = 0; i < 4; ++i) {
;             const size_t row = (size_t)(m0 + wr * 64 + i * 16 + r);
; #pragma unroll
;             for (int j = 0; j < 4; ++j) {
;                 const int col = n0 + wc * 64 + j * 16 + g4 * 4;
;                 const uint2 gm = *(const uint2*)(p.gmb + row * 1024 + col);
;                 const uint2 ga = *(const uint2*)(p.gab + row * 1024 + col);
;                 acc[i][j][0] *= bf_lo(gm.x) * frcp(bf_lo(ga.x)); acc[i][j][1] *= bf_hi(gm.x) * frcp(bf_hi(ga.x));
;                 acc[i][j][2] *= bf_lo(gm.y) * frcp(bf_lo(ga.y)); acc[i][j][3] *= bf_hi(gm.y) * frcp(bf_hi(ga.y));
;             }
;         }
	v_mfma_f32_16x16x32_bf16 v[82:85], v[70:73], v[114:117], v[62:65]
	s_waitcnt lgkmcnt(2)
	v_mfma_f32_16x16x32_bf16 v[94:97], v[130:133], v[114:117], v[58:61]
	s_waitcnt lgkmcnt(1)
	v_mfma_f32_16x16x32_bf16 v[98:101], v[134:137], v[114:117], v[54:57]
	s_waitcnt lgkmcnt(0)
	v_mfma_f32_16x16x32_bf16 v[14:17], v[142:145], v[114:117], v[50:53]
	v_mfma_f32_16x16x32_bf16 v[18:21], v[70:73], v[118:121], v[46:49]
	v_mfma_f32_16x16x32_bf16 v[22:25], v[130:133], v[118:121], v[42:45]
	v_mfma_f32_16x16x32_bf16 v[30:33], v[134:137], v[118:121], v[38:41]
	v_mfma_f32_16x16x32_bf16 v[38:41], v[142:145], v[118:121], v[34:37]
	v_mfma_f32_16x16x32_bf16 v[46:49], v[70:73], v[122:125], v[66:69]
	v_mfma_f32_16x16x32_bf16 v[54:57], v[130:133], v[122:125], v[26:29]
	v_mfma_f32_16x16x32_bf16 v[62:65], v[134:137], v[122:125], v[74:77]
	v_mfma_f32_16x16x32_bf16 v[58:61], v[142:145], v[122:125], v[78:81]
	v_mfma_f32_16x16x32_bf16 v[50:53], v[70:73], v[126:129], v[90:93]
	v_mfma_f32_16x16x32_bf16 v[42:45], v[130:133], v[126:129], v[10:13]
	v_mfma_f32_16x16x32_bf16 v[34:37], v[134:137], v[126:129], v[6:9]
	v_mfma_f32_16x16x32_bf16 v[26:29], v[142:145], v[126:129], v[2:5]
	s_setprio 0
	v_add_u32_e32 v80, s8, v88
	s_nop 0
	v_or_b32_e32 v2, s6, v89
	v_ashrrev_i32_e32 v81, 31, v80
	v_readlane_b32 s40, v214, 50
	v_ashrrev_i32_e32 v3, 31, v2
	v_lshlrev_b64 v[4:5], 11, v[80:81]
	v_readlane_b32 s50, v214, 60
	v_readlane_b32 s51, v214, 61
	v_readlane_b32 s52, v214, 62
	v_readlane_b32 s53, v214, 63
	v_lshl_add_u64 v[6:7], s[50:51], 0, v[4:5]
	v_lshlrev_b64 v[66:67], 1, v[2:3]
	v_lshl_add_u64 v[4:5], s[52:53], 0, v[4:5]
	v_lshl_add_u64 v[68:69], v[4:5], 0, v[66:67]
	s_waitcnt vmcnt(0)
	s_barrier
	global_load_dwordx2 v[4:5], v[68:69], off
	v_lshl_add_u64 v[72:73], v[6:7], 0, v[66:67]
	global_load_dwordx2 v[228:229], v[72:73], off
	global_load_dwordx2 v[230:231], v[72:73], off offset:32
	global_load_dwordx2 v[232:233], v[68:69], off offset:32
	global_load_dwordx2 v[234:235], v[72:73], off offset:64
	global_load_dwordx2 v[236:237], v[68:69], off offset:64
	global_load_dwordx2 v[238:239], v[72:73], off offset:96
	global_load_dwordx2 v[240:241], v[68:69], off offset:96
	v_lshlrev_b64 v[70:71], 10, v[80:81]
	v_readlane_b32 s41, v214, 51
	v_readlane_b32 s42, v214, 52
	v_readlane_b32 s43, v214, 53
	v_readlane_b32 s44, v214, 54
	v_readlane_b32 s45, v214, 55
	v_readlane_b32 s46, v214, 56
	v_readlane_b32 s47, v214, 57
	v_readlane_b32 s48, v214, 58
	v_readlane_b32 s49, v214, 59
	v_readlane_b32 s54, v213, 0
	s_lshl_b64 s[8:9], s[8:9], 11
	v_readlane_b32 s55, v213, 1
	s_add_u32 s12, s54, s8
	s_addc_u32 s13, s55, s9
	s_lshl_b64 s[10:11], s[10:11], 11
	s_waitcnt vmcnt(7)
	v_lshlrev_b32_e32 v0, 16, v4
	v_rcp_f32_e32 v8, v0
	v_and_b32_e32 v0, 0xffff0000, v4
	v_rcp_f32_e32 v9, v0
	v_lshlrev_b32_e32 v0, 16, v5
	v_rcp_f32_e32 v4, v0
	v_and_b32_e32 v0, 0xffff0000, v5
	v_rcp_f32_e32 v5, v0
	s_waitcnt vmcnt(6)
	v_lshlrev_b32_e32 v6, 16, v228
	v_and_b32_e32 v7, 0xffff0000, v228
	v_lshlrev_b32_e32 v2, 16, v229
	v_and_b32_e32 v3, 0xffff0000, v229
	v_pk_mul_f32 v[6:7], v[8:9], v[6:7]
	v_pk_mul_f32 v[2:3], v[4:5], v[2:3]
	s_nop 0
	v_pk_mul_f32 v[4:5], v[84:85], v[2:3]
	v_pk_mul_f32 v[2:3], v[82:83], v[6:7]
	s_waitcnt vmcnt(5)
	v_lshlrev_b32_e32 v10, 16, v230
	s_waitcnt vmcnt(4)
	v_lshlrev_b32_e32 v0, 16, v232
	v_rcp_f32_e32 v12, v0
	v_and_b32_e32 v0, 0xffff0000, v232
	v_rcp_f32_e32 v13, v0
	v_lshlrev_b32_e32 v0, 16, v233
	v_rcp_f32_e32 v8, v0
	v_and_b32_e32 v0, 0xffff0000, v233
	v_rcp_f32_e32 v9, v0
	v_and_b32_e32 v11, 0xffff0000, v230
	v_lshlrev_b32_e32 v6, 16, v231
	v_and_b32_e32 v7, 0xffff0000, v231
	v_pk_mul_f32 v[10:11], v[12:13], v[10:11]
	v_pk_mul_f32 v[6:7], v[8:9], v[6:7]
	s_nop 0
	v_pk_mul_f32 v[8:9], v[96:97], v[6:7]
	v_pk_mul_f32 v[6:7], v[94:95], v[10:11]
	v_mov_b32_e32 v96, v141
	s_waitcnt vmcnt(3)
	v_lshlrev_b32_e32 v74, 16, v234
	s_waitcnt vmcnt(2)
	v_lshlrev_b32_e32 v0, 16, v236
	v_rcp_f32_e32 v76, v0
	v_and_b32_e32 v0, 0xffff0000, v236
	v_rcp_f32_e32 v77, v0
	v_lshlrev_b32_e32 v0, 16, v237
	v_rcp_f32_e32 v12, v0
	v_and_b32_e32 v0, 0xffff0000, v237
	v_rcp_f32_e32 v13, v0
	v_and_b32_e32 v75, 0xffff0000, v234
	v_lshlrev_b32_e32 v10, 16, v235
	v_and_b32_e32 v11, 0xffff0000, v235
	v_pk_mul_f32 v[74:75], v[76:77], v[74:75]
	v_pk_mul_f32 v[10:11], v[12:13], v[10:11]
	s_nop 0
	v_pk_mul_f32 v[12:13], v[100:101], v[10:11]
	v_pk_mul_f32 v[10:11], v[98:99], v[74:75]
	s_nop 0
	s_waitcnt vmcnt(1)
	v_lshlrev_b32_e32 v76, 16, v238
	s_waitcnt vmcnt(0)
	v_lshlrev_b32_e32 v0, 16, v240
	v_rcp_f32_e32 v78, v0
	v_and_b32_e32 v0, 0xffff0000, v240
	v_rcp_f32_e32 v79, v0
	v_lshlrev_b32_e32 v0, 16, v241
	v_rcp_f32_e32 v74, v0
	v_and_b32_e32 v0, 0xffff0000, v241
	v_rcp_f32_e32 v75, v0
	v_and_b32_e32 v77, 0xffff0000, v238
	v_lshlrev_b32_e32 v72, 16, v239
	v_and_b32_e32 v73, 0xffff0000, v239
	v_pk_mul_f32 v[72:73], v[74:75], v[72:73]
	v_pk_mul_f32 v[76:77], v[78:79], v[76:77]
	v_pk_mul_f32 v[16:17], v[16:17], v[72:73]
	v_or_b32_e32 v72, 16, v80
	v_ashrrev_i32_e32 v73, 31, v72
	v_lshlrev_b64 v[74:75], 10, v[72:73]
	v_lshlrev_b64 v[72:73], 11, v[72:73]
	v_pk_mul_f32 v[14:15], v[14:15], v[76:77]
	v_lshl_add_u64 v[76:77], s[50:51], 0, v[72:73]
	v_lshl_add_u64 v[72:73], s[52:53], 0, v[72:73]
	v_lshl_add_u64 v[72:73], v[72:73], 0, v[66:67]
	global_load_dwordx2 v[82:83], v[72:73], off
	v_lshl_add_u64 v[76:77], v[76:77], 0, v[66:67]
	global_load_dwordx2 v[228:229], v[76:77], off
	global_load_dwordx2 v[230:231], v[76:77], off offset:32
	global_load_dwordx2 v[232:233], v[72:73], off offset:32
	global_load_dwordx2 v[234:235], v[76:77], off offset:64
	global_load_dwordx2 v[236:237], v[72:73], off offset:64
	global_load_dwordx2 v[238:239], v[76:77], off offset:96
	global_load_dwordx2 v[240:241], v[72:73], off offset:96
	s_waitcnt vmcnt(7)
; __device__ __forceinline__ float bf_lo(unsigned u) { return __uint_as_float(u << 16); }
; __device__ __forceinline__ float bf_hi(unsigned u) { return __uint_as_float(u & 0xffff0000u); }
; __device__ __forceinline__ float frcp(float x) { return __builtin_amdgcn_rcpf(x); }
; __device__ void phaseC1(const Params& p, int l, char* smem) {
;     ...
; #pragma unroll
;         for (int i = 0; i < 4; ++i) {
;             const size_t row = (size_t)(m0 + wr * 64 + i * 16 + r);
; #pragma unroll
;             for (int j = 0; j < 4; ++j) {
;                 const int col = n0 + wc * 64 + j * 16 + g4 * 4;
;                 const uint2 gm = *(const uint2*)(p.gmb + row * 1024 + col);
;                 const uint2 ga = *(const uint2*)(p.gab + row * 1024 + col);
;                 acc[i][j][0] *= bf_lo(gm.x) * frcp(bf_lo(ga.x)); acc[i][j][1] *= bf_hi(gm.x) * frcp(bf_hi(ga.x));
;                 acc[i][j][2] *= bf_lo(gm.y) * frcp(bf_lo(ga.y)); acc[i][j][3] *= bf_hi(gm.y) * frcp(bf_hi(ga.y));
;             }
;         }
	v_lshlrev_b32_e32 v0, 16, v82
	v_rcp_f32_e32 v86, v0
	v_and_b32_e32 v0, 0xffff0000, v82
	v_rcp_f32_e32 v87, v0
	v_lshlrev_b32_e32 v0, 16, v83
	v_rcp_f32_e32 v82, v0
	v_and_b32_e32 v0, 0xffff0000, v83
	v_rcp_f32_e32 v83, v0
	s_waitcnt vmcnt(6)
	v_lshlrev_b32_e32 v84, 16, v228
	v_and_b32_e32 v85, 0xffff0000, v228
	v_lshlrev_b32_e32 v78, 16, v229
	v_and_b32_e32 v79, 0xffff0000, v229
	v_pk_mul_f32 v[78:79], v[82:83], v[78:79]
	v_pk_mul_f32 v[84:85], v[86:87], v[84:85]
	v_pk_mul_f32 v[20:21], v[20:21], v[78:79]
	v_pk_mul_f32 v[18:19], v[18:19], v[84:85]
	s_waitcnt vmcnt(5)
	v_lshlrev_b32_e32 v84, 16, v230
	s_waitcnt vmcnt(4)
	v_lshlrev_b32_e32 v0, 16, v232
	v_rcp_f32_e32 v86, v0
	v_and_b32_e32 v0, 0xffff0000, v232
	v_rcp_f32_e32 v87, v0
	v_lshlrev_b32_e32 v0, 16, v233
	v_rcp_f32_e32 v82, v0
	v_and_b32_e32 v0, 0xffff0000, v233
	v_rcp_f32_e32 v83, v0
	v_and_b32_e32 v85, 0xffff0000, v230
	v_lshlrev_b32_e32 v78, 16, v231
	v_and_b32_e32 v79, 0xffff0000, v231
	v_pk_mul_f32 v[78:79], v[82:83], v[78:79]
	v_pk_mul_f32 v[84:85], v[86:87], v[84:85]
	v_pk_mul_f32 v[24:25], v[24:25], v[78:79]
	v_pk_mul_f32 v[22:23], v[22:23], v[84:85]
	s_waitcnt vmcnt(3)
	v_lshlrev_b32_e32 v84, 16, v234
	s_waitcnt vmcnt(2)
	v_lshlrev_b32_e32 v0, 16, v236
	v_rcp_f32_e32 v86, v0
	v_and_b32_e32 v0, 0xffff0000, v236
	v_rcp_f32_e32 v87, v0
	v_lshlrev_b32_e32 v0, 16, v237
	v_rcp_f32_e32 v82, v0
	v_and_b32_e32 v0, 0xffff0000, v237
	v_rcp_f32_e32 v83, v0
	v_and_b32_e32 v85, 0xffff0000, v234
	v_lshlrev_b32_e32 v78, 16, v235
	v_and_b32_e32 v79, 0xffff0000, v235
	v_pk_mul_f32 v[78:79], v[82:83], v[78:79]
	v_pk_mul_f32 v[84:85], v[86:87], v[84:85]
	v_pk_mul_f32 v[32:33], v[32:33], v[78:79]
	s_nop 0
	v_pk_mul_f32 v[30:31], v[30:31], v[84:85]
	s_waitcnt vmcnt(1)
	v_lshlrev_b32_e32 v82, 16, v238
	s_waitcnt vmcnt(0)
	v_lshlrev_b32_e32 v0, 16, v240
	v_rcp_f32_e32 v84, v0
	v_and_b32_e32 v0, 0xffff0000, v240
	v_rcp_f32_e32 v85, v0
	v_lshlrev_b32_e32 v0, 16, v241
	v_rcp_f32_e32 v78, v0
	v_and_b32_e32 v0, 0xffff0000, v241
	v_rcp_f32_e32 v79, v0
	v_and_b32_e32 v83, 0xffff0000, v238
	v_lshlrev_b32_e32 v76, 16, v239
	v_and_b32_e32 v77, 0xffff0000, v239
	v_pk_mul_f32 v[76:77], v[78:79], v[76:77]
	v_pk_mul_f32 v[82:83], v[84:85], v[82:83]
	v_pk_mul_f32 v[40:41], v[40:41], v[76:77]
	v_or_b32_e32 v76, 32, v80
	v_ashrrev_i32_e32 v77, 31, v76
	v_lshlrev_b64 v[78:79], 10, v[76:77]
	v_lshlrev_b64 v[76:77], 11, v[76:77]
	v_pk_mul_f32 v[38:39], v[38:39], v[82:83]
	v_lshl_add_u64 v[82:83], s[50:51], 0, v[76:77]
	v_lshl_add_u64 v[76:77], s[52:53], 0, v[76:77]
	v_lshl_add_u64 v[76:77], v[76:77], 0, v[66:67]
	global_load_dwordx2 v[86:87], v[76:77], off
	v_lshl_add_u64 v[82:83], v[82:83], 0, v[66:67]
	global_load_dwordx2 v[228:229], v[82:83], off
	global_load_dwordx2 v[230:231], v[82:83], off offset:32
	global_load_dwordx2 v[232:233], v[76:77], off offset:32
	global_load_dwordx2 v[234:235], v[82:83], off offset:64
	global_load_dwordx2 v[236:237], v[76:77], off offset:64
	global_load_dwordx2 v[238:239], v[82:83], off offset:96
	global_load_dwordx2 v[240:241], v[76:77], off offset:96
	v_or_b32_e32 v80, 48, v80
	v_ashrrev_i32_e32 v81, 31, v80
	s_waitcnt vmcnt(7)
	v_lshlrev_b32_e32 v0, 16, v86
	v_rcp_f32_e32 v92, v0
	v_and_b32_e32 v0, 0xffff0000, v86
	v_rcp_f32_e32 v93, v0
	v_lshlrev_b32_e32 v0, 16, v87
	v_rcp_f32_e32 v86, v0
	v_and_b32_e32 v0, 0xffff0000, v87
	v_rcp_f32_e32 v87, v0
	s_waitcnt vmcnt(6)
	v_lshlrev_b32_e32 v90, 16, v228
	v_and_b32_e32 v91, 0xffff0000, v228
	v_lshlrev_b32_e32 v84, 16, v229
	v_and_b32_e32 v85, 0xffff0000, v229
	v_pk_mul_f32 v[84:85], v[86:87], v[84:85]
	v_pk_mul_f32 v[90:91], v[92:93], v[90:91]
	v_pk_mul_f32 v[48:49], v[48:49], v[84:85]
	v_pk_mul_f32 v[46:47], v[46:47], v[90:91]
	s_waitcnt vmcnt(5)
	v_lshlrev_b32_e32 v90, 16, v230
	s_waitcnt vmcnt(4)
	v_lshlrev_b32_e32 v0, 16, v232
	v_rcp_f32_e32 v92, v0
	v_and_b32_e32 v0, 0xffff0000, v232
	v_rcp_f32_e32 v93, v0
	v_lshlrev_b32_e32 v0, 16, v233
	v_rcp_f32_e32 v86, v0
	v_and_b32_e32 v0, 0xffff0000, v233
	v_rcp_f32_e32 v87, v0
	v_and_b32_e32 v91, 0xffff0000, v230
	v_lshlrev_b32_e32 v84, 16, v231
	v_and_b32_e32 v85, 0xffff0000, v231
	v_pk_mul_f32 v[84:85], v[86:87], v[84:85]
	v_pk_mul_f32 v[90:91], v[92:93], v[90:91]
	v_pk_mul_f32 v[56:57], v[56:57], v[84:85]
	v_pk_mul_f32 v[54:55], v[54:55], v[90:91]
	s_waitcnt vmcnt(3)
	v_lshlrev_b32_e32 v90, 16, v234
	s_waitcnt vmcnt(2)
	v_lshlrev_b32_e32 v0, 16, v236
	v_rcp_f32_e32 v92, v0
	v_and_b32_e32 v0, 0xffff0000, v236
	v_rcp_f32_e32 v93, v0
	v_lshlrev_b32_e32 v0, 16, v237
	v_rcp_f32_e32 v86, v0
	v_and_b32_e32 v0, 0xffff0000, v237
	v_rcp_f32_e32 v87, v0
	v_and_b32_e32 v91, 0xffff0000, v234
	v_lshlrev_b32_e32 v84, 16, v235
	v_and_b32_e32 v85, 0xffff0000, v235
	v_pk_mul_f32 v[84:85], v[86:87], v[84:85]
	v_pk_mul_f32 v[90:91], v[92:93], v[90:91]
	v_pk_mul_f32 v[64:65], v[64:65], v[84:85]
	s_nop 0
	v_pk_mul_f32 v[62:63], v[62:63], v[90:91]
	s_waitcnt vmcnt(1)
	v_lshlrev_b32_e32 v86, 16, v238
	s_waitcnt vmcnt(0)
; __device__ __forceinline__ float bf_lo(unsigned u) { return __uint_as_float(u << 16); }
; __device__ __forceinline__ float bf_hi(unsigned u) { return __uint_as_float(u & 0xffff0000u); }
; __device__ __forceinline__ float frcp(float x) { return __builtin_amdgcn_rcpf(x); }
; __device__ __forceinline__ int opaque_tid() { int t = threadIdx.x; asm volatile("" : "+v"(t)); return t; }
; template <int AMODE>
; __device__ __forceinline__ void gemm_kloop(f32x4 (&acc)[4][4], const u16* __restrict__ A, int lda,
;                                            const u16* __restrict__ Bt, int ldb, int K, char* smem,
;                                            const float* __restrict__ ssq_rows) {
;     const int tid = opaque_tid(), lane = tid & 63, wid = tid >> 6, wr = wid >> 1, wc = wid & 1;
;     const int r = lane & 15, g4 = lane >> 4;
;     char* As = smem; char* Bs = smem + 32768;
;     const int grow = wid * 8 + (lane >> 3);
;     const int gch = ((lane & 7) ^ ((lane >> 3) & 7)) * 8;
;     const u16* Ag = A + (size_t)grow * lda + gch;
;     const u16* Bg = Bt + (size_t)grow * ldb + gch;
;     const int lrow = tid >> 3, lkc = tid & 7;
;     const u16* Ap = A + (size_t)lrow * lda + lkc * 8;
;     const int lds_w = lrow * 128 + ((lkc ^ (lrow & 7)) << 4);
;     uint4 ra[4];
;     float rs[4];
;     const int nk = K >> 6;
;     ...
;     GLOAD(0, 0);
;     LSTORE(0);
;     asm volatile("s_waitcnt vmcnt(0)" ::: "memory");
;     __syncthreads();
; __device__ void phaseC1(const Params& p, int l, char* smem) {
;     ...
; #pragma unroll
;         for (int i = 0; i < 4; ++i) {
;             const size_t row = (size_t)(m0 + wr * 64 + i * 16 + r);
; #pragma unroll
;             for (int j = 0; j < 4; ++j) {
;                 const int col = n0 + wc * 64 + j * 16 + g4 * 4;
;                 const uint2 gm = *(const uint2*)(p.gmb + row * 1024 + col);
;                 const uint2 ga = *(const uint2*)(p.gab + row * 1024 + col);
;                 acc[i][j][0] *= bf_lo(gm.x) * frcp(bf_lo(ga.x)); acc[i][j][1] *= bf_hi(gm.x) * frcp(bf_hi(ga.x));
;                 acc[i][j][2] *= bf_lo(gm.y) * frcp(bf_lo(ga.y)); acc[i][j][3] *= bf_hi(gm.y) * frcp(bf_hi(ga.y));
;             }
;         }
;         gemm_kloop<0>(acc, p.yab + (size_t)m0 * 1024, 1024, p.wt_a + ((size_t)l * 1024 + n0) * 1024, 1024, 1024, smem, nullptr);
	v_lshlrev_b32_e32 v0, 16, v240
	v_rcp_f32_e32 v90, v0
	v_and_b32_e32 v0, 0xffff0000, v240
	v_rcp_f32_e32 v91, v0
	v_lshlrev_b32_e32 v0, 16, v241
	v_rcp_f32_e32 v84, v0
	v_and_b32_e32 v0, 0xffff0000, v241
	v_rcp_f32_e32 v85, v0
	v_and_b32_e32 v87, 0xffff0000, v238
	v_lshlrev_b32_e32 v82, 16, v239
	v_and_b32_e32 v83, 0xffff0000, v239
	v_pk_mul_f32 v[82:83], v[84:85], v[82:83]
	v_pk_mul_f32 v[86:87], v[90:91], v[86:87]
	v_pk_mul_f32 v[60:61], v[60:61], v[82:83]
	v_lshlrev_b64 v[82:83], 10, v[80:81]
	v_lshlrev_b64 v[80:81], 11, v[80:81]
	v_lshl_add_u64 v[84:85], s[50:51], 0, v[80:81]
	v_lshl_add_u64 v[80:81], s[52:53], 0, v[80:81]
	v_lshl_add_u64 v[80:81], v[80:81], 0, v[66:67]
	global_load_dwordx2 v[90:91], v[80:81], off
	v_lshl_add_u64 v[84:85], v[84:85], 0, v[66:67]
	v_pk_mul_f32 v[58:59], v[58:59], v[86:87]
	global_load_dwordx2 v[228:229], v[84:85], off
	global_load_dwordx2 v[230:231], v[84:85], off offset:32
	global_load_dwordx2 v[232:233], v[80:81], off offset:32
	global_load_dwordx2 v[234:235], v[84:85], off offset:64
	global_load_dwordx2 v[236:237], v[80:81], off offset:64
	global_load_dwordx2 v[238:239], v[84:85], off offset:96
	global_load_dwordx2 v[240:241], v[80:81], off offset:96
	v_readlane_b32 s36, v214, 34
	v_readlane_b32 s38, v214, 36
	v_readlane_b32 s39, v214, 37
	s_add_u32 s10, s38, s10
	s_addc_u32 s11, s39, s11
	s_lshl_b64 s[6:7], s[6:7], 11
	v_readlane_b32 s37, v214, 35
	v_readlane_b32 s40, v214, 38
	v_readlane_b32 s41, v214, 39
	v_readlane_b32 s42, v214, 40
	v_readlane_b32 s43, v214, 41
	v_readlane_b32 s44, v214, 42
	v_readlane_b32 s45, v214, 43
	v_readlane_b32 s46, v214, 44
	v_readlane_b32 s47, v214, 45
	v_readlane_b32 s48, v214, 46
	v_readlane_b32 s49, v214, 47
	v_readlane_b32 s50, v214, 48
	v_readlane_b32 s51, v214, 49
	s_waitcnt vmcnt(7)
	v_lshlrev_b32_e32 v0, 16, v90
	v_rcp_f32_e32 v94, v0
	v_and_b32_e32 v0, 0xffff0000, v90
	v_rcp_f32_e32 v95, v0
	v_lshlrev_b32_e32 v0, 16, v91
	v_rcp_f32_e32 v90, v0
	v_and_b32_e32 v0, 0xffff0000, v91
	v_rcp_f32_e32 v91, v0
	s_waitcnt vmcnt(6)
	v_lshlrev_b32_e32 v92, 16, v228
	v_and_b32_e32 v93, 0xffff0000, v228
	v_lshlrev_b32_e32 v86, 16, v229
	v_and_b32_e32 v87, 0xffff0000, v229
	v_pk_mul_f32 v[86:87], v[90:91], v[86:87]
	v_pk_mul_f32 v[92:93], v[94:95], v[92:93]
	v_pk_mul_f32 v[52:53], v[52:53], v[86:87]
	v_pk_mul_f32 v[50:51], v[50:51], v[92:93]
	s_waitcnt vmcnt(5)
	v_lshlrev_b32_e32 v92, 16, v230
	s_waitcnt vmcnt(4)
	v_lshlrev_b32_e32 v0, 16, v232
	v_rcp_f32_e32 v94, v0
	v_and_b32_e32 v0, 0xffff0000, v232
	v_rcp_f32_e32 v95, v0
	v_lshlrev_b32_e32 v0, 16, v233
	v_rcp_f32_e32 v90, v0
	v_and_b32_e32 v0, 0xffff0000, v233
	v_rcp_f32_e32 v91, v0
	v_and_b32_e32 v93, 0xffff0000, v230
	v_lshlrev_b32_e32 v86, 16, v231
	v_and_b32_e32 v87, 0xffff0000, v231
	v_pk_mul_f32 v[86:87], v[90:91], v[86:87]
	v_pk_mul_f32 v[92:93], v[94:95], v[92:93]
	v_pk_mul_f32 v[44:45], v[44:45], v[86:87]
	v_pk_mul_f32 v[42:43], v[42:43], v[92:93]
	s_waitcnt vmcnt(3)
	v_lshlrev_b32_e32 v92, 16, v234
	s_waitcnt vmcnt(2)
	v_lshlrev_b32_e32 v0, 16, v236
	v_rcp_f32_e32 v94, v0
	v_and_b32_e32 v0, 0xffff0000, v236
	v_rcp_f32_e32 v95, v0
	v_lshlrev_b32_e32 v0, 16, v237
	v_rcp_f32_e32 v90, v0
	v_and_b32_e32 v0, 0xffff0000, v237
	v_rcp_f32_e32 v91, v0
	v_and_b32_e32 v93, 0xffff0000, v234
	v_lshlrev_b32_e32 v86, 16, v235
	v_and_b32_e32 v87, 0xffff0000, v235
	v_pk_mul_f32 v[86:87], v[90:91], v[86:87]
	v_pk_mul_f32 v[92:93], v[94:95], v[92:93]
	v_pk_mul_f32 v[36:37], v[36:37], v[86:87]
	s_nop 0
	v_pk_mul_f32 v[34:35], v[34:35], v[92:93]
	s_waitcnt vmcnt(1)
	v_lshlrev_b32_e32 v90, 16, v238
	s_waitcnt vmcnt(0)
	v_lshlrev_b32_e32 v0, 16, v240
	v_rcp_f32_e32 v92, v0
	v_and_b32_e32 v0, 0xffff0000, v240
	v_rcp_f32_e32 v93, v0
	v_lshlrev_b32_e32 v0, 16, v241
	v_rcp_f32_e32 v86, v0
	v_and_b32_e32 v0, 0xffff0000, v241
	v_rcp_f32_e32 v87, v0
	v_and_b32_e32 v91, 0xffff0000, v238
	v_lshlrev_b32_e32 v84, 16, v239
	v_and_b32_e32 v85, 0xffff0000, v239
	v_pk_mul_f32 v[84:85], v[86:87], v[84:85]
	v_ashrrev_i32_e32 v94, 6, v96
	v_bfe_u32 v0, v96, 3, 3
	v_pk_mul_f32 v[28:29], v[28:29], v[84:85]
	v_lshl_or_b32 v84, v94, 3, v0
	v_ashrrev_i32_e32 v85, 31, v84
	v_pk_mul_f32 v[90:91], v[92:93], v[90:91]
	v_bitop3_b32 v0, v0, v96, 7 bitop3:0x78
	v_lshlrev_b64 v[86:87], 11, v[84:85]
	v_pk_mul_f32 v[26:27], v[26:27], v[90:91]
	v_lshlrev_b32_e32 v0, 4, v0
	v_lshl_add_u64 v[90:91], s[10:11], 0, v[86:87]
	v_lshl_add_u64 v[92:93], v[90:91], 0, v[0:1]
	v_lshlrev_b32_e32 v90, 10, v94
	v_add_u32_e32 v91, 0x8000, v90
	v_lshl_add_u64 v[84:85], s[12:13], 0, v[86:87]
	v_readfirstlane_b32 s10, v91
	s_mov_b32 m0, s10
	v_readfirstlane_b32 s10, v90
	v_add_u32_e32 v91, 0x9000, v90
	v_lshl_add_u64 v[84:85], v[84:85], 0, v[0:1]
	global_load_lds_dwordx4 v[92:93], off
	s_mov_b32 m0, s10
	s_mov_b64 s[12:13], 0x10000
	v_readfirstlane_b32 s10, v91
	v_add_u32_e32 v91, 0x1000, v90
	global_load_lds_dwordx4 v[84:85], off
	v_lshl_add_u64 v[94:95], v[92:93], 0, s[12:13]
	s_mov_b32 m0, s10
	v_readfirstlane_b32 s10, v91
	v_add_u32_e32 v91, 0xa000, v90
	global_load_lds_dwordx4 v[94:95], off
	v_lshl_add_u64 v[94:95], v[84:85], 0, s[12:13]
	s_mov_b32 m0, s10
	s_mov_b64 s[12:13], 0x20000
	v_readfirstlane_b32 s10, v91
	v_add_u32_e32 v91, 0x2000, v90
	global_load_lds_dwordx4 v[94:95], off
	v_lshl_add_u64 v[94:95], v[92:93], 0, s[12:13]
	s_mov_b32 m0, s10
	v_readfirstlane_b32 s10, v91
	v_add_u32_e32 v91, 0xb000, v90
	global_load_lds_dwordx4 v[94:95], off
	v_lshl_add_u64 v[94:95], v[84:85], 0, s[12:13]
	s_mov_b32 m0, s10
	s_mov_b64 s[12:13], 0x30000
	v_readfirstlane_b32 s10, v91
	v_add_u32_e32 v91, 0x3000, v90
	global_load_lds_dwordx4 v[94:95], off
	v_lshl_add_u64 v[92:93], v[92:93], 0, s[12:13]
	s_mov_b32 m0, s10
	v_readfirstlane_b32 s10, v91
	global_load_lds_dwordx4 v[92:93], off
	v_lshl_add_u64 v[84:85], v[84:85], 0, s[12:13]
	s_mov_b32 m0, s10
	v_lshrrev_b32_e32 v91, 1, v96
	global_load_lds_dwordx4 v[84:85], off
	v_and_b32_e32 v85, 15, v96
	s_mov_b32 s10, 0x1ffffc0
	v_and_or_b32 v85, v91, s10, v85
	v_and_b32_e32 v97, 7, v96
	v_bfe_u32 v84, v96, 4, 2
	v_lshlrev_b32_e32 v92, 7, v85
	v_lshlrev_b32_e32 v85, 7, v96
	v_and_b32_e32 v91, 0x2780, v85
	v_bitop3_b32 v85, v84, v96, 7 bitop3:0x78
	v_bitop3_b32 v84, v84, v97, 4 bitop3:0x36
	s_waitcnt vmcnt(0)
	v_lshlrev_b32_e32 v94, 4, v85
	v_lshlrev_b32_e32 v93, 4, v84
	v_lshl_add_u64 v[84:85], s[6:7], 0, v[86:87]
	v_lshl_add_u64 v[86:87], s[8:9], 0, v[86:87]
	v_or_b32_e32 v84, v84, v0
	v_or_b32_e32 v86, v86, v0
	v_lshl_add_u64 v[84:85], s[4:5], 0, v[84:85]
	v_lshl_add_u64 v[86:87], s[54:55], 0, v[86:87]
	s_mov_b64 s[6:7], 0
	s_mov_b32 s8, 0
	s_waitcnt vmcnt(0) lgkmcnt(0)
	s_barrier
; __device__ __forceinline__ int opaque_tid() { int t = threadIdx.x; asm volatile("" : "+v"(t)); return t; }
; template <int AMODE>
; __device__ __forceinline__ void gemm_kloop(f32x4 (&acc)[4][4], const u16* __restrict__ A, int lda,
;                                            const u16* __restrict__ Bt, int ldb, int K, char* smem,
;                                            const float* __restrict__ ssq_rows) {
;     const int tid = opaque_tid(), lane = tid & 63, wid = tid >> 6, wr = wid >> 1, wc = wid & 1;
;     const int r = lane & 15, g4 = lane >> 4;
;     char* As = smem; char* Bs = smem + 32768;
;     const int grow = wid * 8 + (lane >> 3);
;     const int gch = ((lane & 7) ^ ((lane >> 3) & 7)) * 8;
;     const u16* Ag = A + (size_t)grow * lda + gch;
;     const u16* Bg = Bt + (size_t)grow * ldb + gch;
;     const int lrow = tid >> 3, lkc = tid & 7;
;     const u16* Ap = A + (size_t)lrow * lda + lkc * 8;
;     const int lds_w = lrow * 128 + ((lkc ^ (lrow & 7)) << 4);
;     uint4 ra[4];
;     float rs[4];
;     const int nk = K >> 6;
;     ...
;     GLOAD(0, 0);
;     LSTORE(0);
;     asm volatile("s_waitcnt vmcnt(0)" ::: "memory");
;     __syncthreads();
;     for (int kt = 0; kt < nk; ++kt) {
;         const int buf = kt & 1;
;         if (kt + 1 < nk) GLOAD(kt + 1, buf ^ 1);
;         const char* ab = As + buf * 16384 + (wr * 64 + r) * 128;
;         const char* bb = Bs + buf * 16384 + (wc * 64 + r) * 128;
;         bf16x8 af[2][4], bfr[2][4];
; #pragma unroll
;         for (int ks = 0; ks < 2; ++ks) {
;             const int co = ((ks * 4 + g4) ^ (r & 7)) << 4;
; #pragma unroll
;             for (int i = 0; i < 4; ++i) af[ks][i] = ld_frag(ab + i * 2048 + co);
; #pragma unroll
;             for (int j = 0; j < 4; ++j) bfr[ks][j] = ld_frag(bb + j * 2048 + co);
;         }
;         __builtin_amdgcn_sched_barrier(0);
;         __builtin_amdgcn_s_setprio(1);
; #pragma unroll
;         for (int ks = 0; ks < 2; ++ks)
; #pragma unroll
;             for (int i = 0; i < 4; ++i)
; #pragma unroll
;                 for (int j = 0; j < 4; ++j) acc[i][j] = MFMA(bfr[ks][j], af[ks][i], acc[i][j]);
;         __builtin_amdgcn_s_setprio(0);
;         __builtin_amdgcn_sched_barrier(0);
;         if (kt + 1 < nk) LSTORE(buf ^ 1);
;         asm volatile("s_waitcnt vmcnt(0)" ::: "memory");
;         __syncthreads();
;     }
	v_lshrrev_b32_e32 v220, 6, v141
	v_bfe_u32 v221, v141, 3, 3
	v_lshl_or_b32 v216, v220, 3, v221
	v_and_b32_e32 v222, 7, v141
	v_xor_b32_e32 v222, v222, v221
	v_lshlrev_b32_e32 v222, 4, v222
	v_lshl_or_b32 v216, v216, 11, v222
	v_add_u32_e32 v217, 0x10000, v216
	v_add_u32_e32 v218, 0x20000, v216
	v_add_u32_e32 v219, 0x30000, v216
	v_readfirstlane_b32 s10, v220
	s_lshl_b32 s10, s10, 14
	v_readfirstlane_b32 s100, v84
	v_readfirstlane_b32 s101, v85
	s_sub_u32 s100, s100, s10
	s_subb_u32 s101, s101, 0
	v_readfirstlane_b32 s98, v86
	v_readfirstlane_b32 s99, v87
	s_sub_u32 s98, s98, s10
	s_subb_u32 s99, s99, 0
.LBB0_709:
	s_setprio 1
	s_and_b32 s9, s8, 0x4000
	s_xor_b32 s10, s9, 0x4000
	v_add_u32_e32 v0, s10, v90
	s_add_u32 s100, s100, 0x80
	s_addc_u32 s101, s101, 0
	s_add_u32 s98, s98, 0x80
	s_addc_u32 s99, s99, 0
	v_readfirstlane_b32 s10, v0
	s_add_u32 m0, s10, 0x8000
	v_add_u32_e32 v0, s9, v92
	global_load_lds_dwordx4 v216, s[100:101]
	v_or_b32_e32 v95, s9, v91
	s_add_u32 m0, s10, 0x0
	v_add_u32_e32 v114, v0, v94
	global_load_lds_dwordx4 v216, s[98:99]
	v_add_u32_e32 v130, v95, v94
	s_add_u32 m0, s10, 0x9000
	v_add_u32_e32 v0, v0, v93
	global_load_lds_dwordx4 v217, s[100:101]
	ds_read_b128 v[96:99], v114
	s_add_u32 m0, s10, 0x1000
	ds_read_b128 v[100:103], v114 offset:2048
	global_load_lds_dwordx4 v217, s[98:99]
	ds_read_b128 v[110:113], v114 offset:4096
	s_add_u32 m0, s10, 0xa000
	ds_read_b128 v[114:117], v114 offset:6144
	global_load_lds_dwordx4 v218, s[100:101]
	ds_read_b128 v[118:121], v130 offset:32768
	s_add_u32 m0, s10, 0x2000
	ds_read_b128 v[122:125], v130 offset:34816
	global_load_lds_dwordx4 v218, s[98:99]
	ds_read_b128 v[126:129], v130 offset:36864
	s_add_u32 m0, s10, 0xb000
	ds_read_b128 v[130:133], v130 offset:38912
	global_load_lds_dwordx4 v219, s[100:101]
	ds_read_b128 v[134:137], v0
	s_add_u32 m0, s10, 0x3000
	ds_read_b128 v[142:145], v0 offset:2048
	global_load_lds_dwordx4 v219, s[98:99]
	ds_read_b128 v[146:149], v0 offset:4096
	ds_read_b128 v[150:153], v0 offset:6144
	v_add_u32_e32 v0, v95, v93
	ds_read_b128 v[172:175], v0 offset:32768
	ds_read_b128 v[176:179], v0 offset:34816
	ds_read_b128 v[180:183], v0 offset:36864
	ds_read_b128 v[184:187], v0 offset:38912
	s_setprio 0
	s_waitcnt lgkmcnt(0)
	v_mfma_f32_16x16x32_bf16 v[2:5], v[118:121], v[96:99], v[2:5]
	v_mfma_f32_16x16x32_bf16 v[6:9], v[122:125], v[96:99], v[6:9]
	v_mfma_f32_16x16x32_bf16 v[10:13], v[126:129], v[96:99], v[10:13]
	v_mfma_f32_16x16x32_bf16 v[14:17], v[130:133], v[96:99], v[14:17]
	v_mfma_f32_16x16x32_bf16 v[18:21], v[118:121], v[100:103], v[18:21]
	v_mfma_f32_16x16x32_bf16 v[22:25], v[122:125], v[100:103], v[22:25]
	v_mfma_f32_16x16x32_bf16 v[30:33], v[126:129], v[100:103], v[30:33]
	v_mfma_f32_16x16x32_bf16 v[38:41], v[130:133], v[100:103], v[38:41]
	v_mfma_f32_16x16x32_bf16 v[46:49], v[118:121], v[110:113], v[46:49]
	v_mfma_f32_16x16x32_bf16 v[54:57], v[122:125], v[110:113], v[54:57]
	v_mfma_f32_16x16x32_bf16 v[62:65], v[126:129], v[110:113], v[62:65]
	v_mfma_f32_16x16x32_bf16 v[58:61], v[130:133], v[110:113], v[58:61]
	v_mfma_f32_16x16x32_bf16 v[50:53], v[118:121], v[114:117], v[50:53]
	v_mfma_f32_16x16x32_bf16 v[42:45], v[122:125], v[114:117], v[42:45]
	v_mfma_f32_16x16x32_bf16 v[34:37], v[126:129], v[114:117], v[34:37]
	v_mfma_f32_16x16x32_bf16 v[26:29], v[130:133], v[114:117], v[26:29]
	v_mfma_f32_16x16x32_bf16 v[2:5], v[172:175], v[134:137], v[2:5]
	v_mfma_f32_16x16x32_bf16 v[6:9], v[176:179], v[134:137], v[6:9]
	v_mfma_f32_16x16x32_bf16 v[10:13], v[180:183], v[134:137], v[10:13]
	v_mfma_f32_16x16x32_bf16 v[14:17], v[184:187], v[134:137], v[14:17]
	v_mfma_f32_16x16x32_bf16 v[18:21], v[172:175], v[142:145], v[18:21]
	v_mfma_f32_16x16x32_bf16 v[22:25], v[176:179], v[142:145], v[22:25]
	v_mfma_f32_16x16x32_bf16 v[30:33], v[180:183], v[142:145], v[30:33]
	v_mfma_f32_16x16x32_bf16 v[38:41], v[184:187], v[142:145], v[38:41]
	v_mfma_f32_16x16x32_bf16 v[46:49], v[172:175], v[146:149], v[46:49]
	v_mfma_f32_16x16x32_bf16 v[54:57], v[176:179], v[146:149], v[54:57]
	v_mfma_f32_16x16x32_bf16 v[62:65], v[180:183], v[146:149], v[62:65]
	v_mfma_f32_16x16x32_bf16 v[58:61], v[184:187], v[146:149], v[58:61]
	v_mfma_f32_16x16x32_bf16 v[50:53], v[172:175], v[150:153], v[50:53]
	v_mfma_f32_16x16x32_bf16 v[42:45], v[176:179], v[150:153], v[42:45]
	v_mfma_f32_16x16x32_bf16 v[34:37], v[180:183], v[150:153], v[34:37]
	v_mfma_f32_16x16x32_bf16 v[26:29], v[184:187], v[150:153], v[26:29]
	s_nop 0
	s_waitcnt vmcnt(0)
	s_add_u32 s6, s6, 0x80
	s_addc_u32 s7, s7, 0
	s_addk_i32 s8, 0x4000
	s_cmpk_eq_i32 s6, 0x780
	s_waitcnt vmcnt(0)
	s_barrier
	s_cbranch_scc0 .LBB0_709
; __device__ __forceinline__ float bf_lo(unsigned u) { return __uint_as_float(u << 16); }
; __device__ __forceinline__ float bf_hi(unsigned u) { return __uint_as_float(u & 0xffff0000u); }
; template <int AMODE>
; __device__ __forceinline__ void gemm_kloop(f32x4 (&acc)[4][4], const u16* __restrict__ A, int lda,
;                                            const u16* __restrict__ Bt, int ldb, int K, char* smem,
;                                            const float* __restrict__ ssq_rows) {
;     ...
;     for (int kt = 0; kt < nk; ++kt) {
;         const int buf = kt & 1;
;         if (kt + 1 < nk) GLOAD(kt + 1, buf ^ 1);
;         const char* ab = As + buf * 16384 + (wr * 64 + r) * 128;
;         const char* bb = Bs + buf * 16384 + (wc * 64 + r) * 128;
;         bf16x8 af[2][4], bfr[2][4];
; #pragma unroll
;         for (int ks = 0; ks < 2; ++ks) {
;             const int co = ((ks * 4 + g4) ^ (r & 7)) << 4;
; #pragma unroll
;             for (int i = 0; i < 4; ++i) af[ks][i] = ld_frag(ab + i * 2048 + co);
; #pragma unroll
;             for (int j = 0; j < 4; ++j) bfr[ks][j] = ld_frag(bb + j * 2048 + co);
;         }
;         __builtin_amdgcn_sched_barrier(0);
;         __builtin_amdgcn_s_setprio(1);
; #pragma unroll
;         for (int ks = 0; ks < 2; ++ks)
; #pragma unroll
;             for (int i = 0; i < 4; ++i)
; #pragma unroll
;                 for (int j = 0; j < 4; ++j) acc[i][j] = MFMA(bfr[ks][j], af[ks][i], acc[i][j]);
;         __builtin_amdgcn_s_setprio(0);
;         __builtin_amdgcn_sched_barrier(0);
;         if (kt + 1 < nk) LSTORE(buf ^ 1);
;         asm volatile("s_waitcnt vmcnt(0)" ::: "memory");
;         __syncthreads();
;     }
; __device__ void phaseC1(const Params& p, int l, char* smem) {
;     ...
; #pragma unroll
;         for (int i = 0; i < 4; ++i) {
;             const size_t row = (size_t)(m0 + wr * 64 + i * 16 + r);
; #pragma unroll
;             for (int j = 0; j < 4; ++j) {
;                 const int col = n0 + wc * 64 + j * 16 + g4 * 4;
;                 const uint2 ga = *(const uint2*)(p.gab + row * 1024 + col);
;                 *(uint2*)(p.ub + row * 1024 + col) =
;                     make_uint2(pk2(acc[i][j][0] * bf_lo(ga.x), acc[i][j][1] * bf_hi(ga.x)),
;                                pk2(acc[i][j][2] * bf_lo(ga.y), acc[i][j][3] * bf_hi(ga.y)));
;             }
	v_add_u32_e32 v0, v92, v94
	ds_read_b128 v[84:87], v0 offset:16384
	ds_read_b128 v[96:99], v0 offset:18432
	ds_read_b128 v[100:103], v0 offset:20480
	ds_read_b128 v[110:113], v0 offset:22528
	v_add_u32_e32 v0, v91, v94
	ds_read_b128 v[114:117], v0 offset:49152
	ds_read_b128 v[118:121], v0 offset:51200
	ds_read_b128 v[122:125], v0 offset:53248
	ds_read_b128 v[126:129], v0 offset:55296
	v_add_u32_e32 v0, v92, v93
	ds_read_b128 v[130:133], v0 offset:16384
	ds_read_b128 v[134:137], v0 offset:18432
	ds_read_b128 v[142:145], v0 offset:20480
	ds_read_b128 v[146:149], v0 offset:22528
	v_add_u32_e32 v0, v91, v93
	ds_read_b128 v[90:93], v0 offset:49152
	ds_read_b128 v[150:153], v0 offset:51200
	ds_read_b128 v[172:175], v0 offset:53248
	ds_read_b128 v[176:179], v0 offset:55296
	s_setprio 1
	s_waitcnt lgkmcnt(11)
	v_mfma_f32_16x16x32_bf16 v[2:5], v[114:117], v[84:87], v[2:5]
	s_waitcnt lgkmcnt(10)
	v_mfma_f32_16x16x32_bf16 v[6:9], v[118:121], v[84:87], v[6:9]
	s_waitcnt lgkmcnt(9)
	v_mfma_f32_16x16x32_bf16 v[10:13], v[122:125], v[84:87], v[10:13]
	s_waitcnt lgkmcnt(8)
	v_mfma_f32_16x16x32_bf16 v[14:17], v[126:129], v[84:87], v[14:17]
	v_mfma_f32_16x16x32_bf16 v[18:21], v[114:117], v[96:99], v[18:21]
	v_mfma_f32_16x16x32_bf16 v[22:25], v[118:121], v[96:99], v[22:25]
	v_mfma_f32_16x16x32_bf16 v[30:33], v[122:125], v[96:99], v[30:33]
	v_mfma_f32_16x16x32_bf16 v[84:87], v[126:129], v[96:99], v[38:41]
	v_mfma_f32_16x16x32_bf16 v[46:49], v[114:117], v[100:103], v[46:49]
	v_mfma_f32_16x16x32_bf16 v[54:57], v[118:121], v[100:103], v[54:57]
	v_mfma_f32_16x16x32_bf16 v[62:65], v[122:125], v[100:103], v[62:65]
	v_mfma_f32_16x16x32_bf16 v[58:61], v[126:129], v[100:103], v[58:61]
	v_mfma_f32_16x16x32_bf16 v[50:53], v[114:117], v[110:113], v[50:53]
	v_mfma_f32_16x16x32_bf16 v[94:97], v[118:121], v[110:113], v[42:45]
	v_mfma_f32_16x16x32_bf16 v[98:101], v[122:125], v[110:113], v[34:37]
	v_mfma_f32_16x16x32_bf16 v[110:113], v[126:129], v[110:113], v[26:29]
	s_waitcnt lgkmcnt(3)
	v_mfma_f32_16x16x32_bf16 v[114:117], v[90:93], v[130:133], v[2:5]
	s_waitcnt lgkmcnt(2)
	v_mfma_f32_16x16x32_bf16 v[118:121], v[150:153], v[130:133], v[6:9]
	s_waitcnt lgkmcnt(1)
	v_mfma_f32_16x16x32_bf16 v[122:125], v[172:175], v[130:133], v[10:13]
	s_waitcnt lgkmcnt(0)
	v_mfma_f32_16x16x32_bf16 v[126:129], v[176:179], v[130:133], v[14:17]
	v_mfma_f32_16x16x32_bf16 v[130:133], v[90:93], v[134:137], v[18:21]
	v_mfma_f32_16x16x32_bf16 v[42:45], v[150:153], v[134:137], v[22:25]
	v_mfma_f32_16x16x32_bf16 v[38:41], v[172:175], v[134:137], v[30:33]
	v_mfma_f32_16x16x32_bf16 v[34:37], v[176:179], v[134:137], v[84:87]
	v_mfma_f32_16x16x32_bf16 v[30:33], v[90:93], v[142:145], v[46:49]
	v_mfma_f32_16x16x32_bf16 v[26:29], v[150:153], v[142:145], v[54:57]
	v_mfma_f32_16x16x32_bf16 v[22:25], v[172:175], v[142:145], v[62:65]
	v_mfma_f32_16x16x32_bf16 v[18:21], v[176:179], v[142:145], v[58:61]
	v_mfma_f32_16x16x32_bf16 v[14:17], v[90:93], v[146:149], v[50:53]
	v_mfma_f32_16x16x32_bf16 v[10:13], v[150:153], v[146:149], v[94:97]
	v_mfma_f32_16x16x32_bf16 v[6:9], v[172:175], v[146:149], v[98:101]
	v_mfma_f32_16x16x32_bf16 v[2:5], v[176:179], v[146:149], v[110:113]
	s_setprio 0
	s_waitcnt vmcnt(0)
	s_barrier
	global_load_dwordx2 v[228:229], v[68:69], off
	global_load_dwordx2 v[230:231], v[68:69], off offset:32
	global_load_dwordx2 v[232:233], v[68:69], off offset:64
	global_load_dwordx2 v[234:235], v[68:69], off offset:96
	v_readlane_b32 s36, v213, 4
	v_readlane_b32 s37, v213, 5
	v_readlane_b32 s38, v213, 6
	v_readlane_b32 s39, v213, 7
	v_readlane_b32 s40, v213, 8
	v_readlane_b32 s41, v213, 9
	v_readlane_b32 s42, v213, 10
	v_readlane_b32 s43, v213, 11
	v_readlane_b32 s44, v213, 12
	v_readlane_b32 s45, v213, 13
	v_readlane_b32 s46, v213, 14
	v_readlane_b32 s47, v213, 15
	v_readlane_b32 s48, v213, 16
	v_readlane_b32 s49, v213, 17
	v_readlane_b32 s50, v213, 18
	v_readlane_b32 s51, v213, 19
	s_waitcnt vmcnt(3)
	v_lshlrev_b32_e32 v48, 16, v228
	v_and_b32_e32 v49, 0xffff0000, v228
	v_pk_mul_f32 v[48:49], v[114:115], v[48:49]
	s_nop 0
	v_cvt_pk_bf16_f32 v46, v48, v49
	v_lshlrev_b32_e32 v48, 16, v229
	v_and_b32_e32 v49, 0xffff0000, v229
	v_pk_mul_f32 v[48:49], v[116:117], v[48:49]
	s_nop 0
	v_cvt_pk_bf16_f32 v47, v48, v49
	v_lshl_add_u64 v[48:49], v[70:71], 1, s[36:37]
	v_lshl_add_u64 v[48:49], v[48:49], 0, v[66:67]
	global_store_dwordx2 v[48:49], v[46:47], off
	s_waitcnt vmcnt(3)
	v_lshlrev_b32_e32 v50, 16, v230
	v_and_b32_e32 v51, 0xffff0000, v230
	v_pk_mul_f32 v[50:51], v[118:119], v[50:51]
	s_nop 0
	v_cvt_pk_bf16_f32 v46, v50, v51
	v_lshlrev_b32_e32 v50, 16, v231
	v_and_b32_e32 v51, 0xffff0000, v231
	v_pk_mul_f32 v[50:51], v[120:121], v[50:51]
	s_nop 0
	v_cvt_pk_bf16_f32 v47, v50, v51
	global_store_dwordx2 v[48:49], v[46:47], off offset:32
	s_waitcnt vmcnt(3)
	v_lshlrev_b32_e32 v50, 16, v232
	v_and_b32_e32 v51, 0xffff0000, v232
	v_pk_mul_f32 v[50:51], v[122:123], v[50:51]
	s_nop 0
	v_cvt_pk_bf16_f32 v46, v50, v51
	v_lshlrev_b32_e32 v50, 16, v233
	v_and_b32_e32 v51, 0xffff0000, v233
	v_pk_mul_f32 v[50:51], v[124:125], v[50:51]
	s_nop 0
	v_cvt_pk_bf16_f32 v47, v50, v51
	global_store_dwordx2 v[48:49], v[46:47], off offset:64
	s_waitcnt vmcnt(3)
; __device__ __forceinline__ float bf_lo(unsigned u) { return __uint_as_float(u << 16); }
; __device__ __forceinline__ float bf_hi(unsigned u) { return __uint_as_float(u & 0xffff0000u); }
; __device__ void phaseC1(const Params& p, int l, char* smem) {
;     ...
; #pragma unroll
;         for (int i = 0; i < 4; ++i) {
;             const size_t row = (size_t)(m0 + wr * 64 + i * 16 + r);
; #pragma unroll
;             for (int j = 0; j < 4; ++j) {
;                 const int col = n0 + wc * 64 + j * 16 + g4 * 4;
;                 const uint2 ga = *(const uint2*)(p.gab + row * 1024 + col);
;                 *(uint2*)(p.ub + row * 1024 + col) =
;                     make_uint2(pk2(acc[i][j][0] * bf_lo(ga.x), acc[i][j][1] * bf_hi(ga.x)),
;                                pk2(acc[i][j][2] * bf_lo(ga.y), acc[i][j][3] * bf_hi(ga.y)));
;             }
	v_lshlrev_b32_e32 v50, 16, v234
	v_and_b32_e32 v51, 0xffff0000, v234
	v_pk_mul_f32 v[50:51], v[126:127], v[50:51]
	s_nop 0
	v_cvt_pk_bf16_f32 v46, v50, v51
	v_lshlrev_b32_e32 v50, 16, v235
	v_and_b32_e32 v51, 0xffff0000, v235
	v_pk_mul_f32 v[50:51], v[128:129], v[50:51]
	s_nop 0
	v_cvt_pk_bf16_f32 v47, v50, v51
	global_store_dwordx2 v[48:49], v[46:47], off offset:96
	global_load_dwordx2 v[228:229], v[72:73], off
	global_load_dwordx2 v[230:231], v[72:73], off offset:32
	global_load_dwordx2 v[232:233], v[72:73], off offset:64
	global_load_dwordx2 v[234:235], v[72:73], off offset:96
	s_waitcnt vmcnt(3)
	v_lshlrev_b32_e32 v48, 16, v228
	v_and_b32_e32 v49, 0xffff0000, v228
	v_pk_mul_f32 v[48:49], v[130:131], v[48:49]
	s_nop 0
	v_cvt_pk_bf16_f32 v46, v48, v49
	v_lshlrev_b32_e32 v48, 16, v229
	v_and_b32_e32 v49, 0xffff0000, v229
	v_pk_mul_f32 v[48:49], v[132:133], v[48:49]
	s_nop 0
	v_cvt_pk_bf16_f32 v47, v48, v49
	v_lshl_add_u64 v[48:49], v[74:75], 1, s[36:37]
	v_lshl_add_u64 v[48:49], v[48:49], 0, v[66:67]
	global_store_dwordx2 v[48:49], v[46:47], off
	s_waitcnt vmcnt(3)
	v_lshlrev_b32_e32 v50, 16, v230
	v_and_b32_e32 v51, 0xffff0000, v230
	v_lshlrev_b32_e32 v46, 16, v231
	v_and_b32_e32 v47, 0xffff0000, v231
	v_pk_mul_f32 v[42:43], v[42:43], v[50:51]
	v_pk_mul_f32 v[44:45], v[44:45], v[46:47]
	v_cvt_pk_bf16_f32 v42, v42, v43
	v_cvt_pk_bf16_f32 v43, v44, v45
	global_store_dwordx2 v[48:49], v[42:43], off offset:32
	s_waitcnt vmcnt(3)
	v_lshlrev_b32_e32 v44, 16, v232
	v_and_b32_e32 v45, 0xffff0000, v232
	v_lshlrev_b32_e32 v42, 16, v233
	v_and_b32_e32 v43, 0xffff0000, v233
	v_pk_mul_f32 v[38:39], v[38:39], v[44:45]
	v_pk_mul_f32 v[40:41], v[40:41], v[42:43]
	v_cvt_pk_bf16_f32 v38, v38, v39
	v_cvt_pk_bf16_f32 v39, v40, v41
	global_store_dwordx2 v[48:49], v[38:39], off offset:64
	s_waitcnt vmcnt(3)
	v_lshlrev_b32_e32 v40, 16, v234
	v_and_b32_e32 v41, 0xffff0000, v234
	v_lshlrev_b32_e32 v38, 16, v235
	v_and_b32_e32 v39, 0xffff0000, v235
	v_pk_mul_f32 v[34:35], v[34:35], v[40:41]
	v_pk_mul_f32 v[36:37], v[36:37], v[38:39]
	v_cvt_pk_bf16_f32 v34, v34, v35
	v_cvt_pk_bf16_f32 v35, v36, v37
	global_store_dwordx2 v[48:49], v[34:35], off offset:96
	global_load_dwordx2 v[228:229], v[76:77], off
	global_load_dwordx2 v[230:231], v[76:77], off offset:32
	global_load_dwordx2 v[232:233], v[76:77], off offset:64
	global_load_dwordx2 v[234:235], v[76:77], off offset:96
	s_waitcnt vmcnt(3)
	v_lshlrev_b32_e32 v36, 16, v228
	v_and_b32_e32 v37, 0xffff0000, v228
	v_lshlrev_b32_e32 v34, 16, v229
	v_and_b32_e32 v35, 0xffff0000, v229
	v_pk_mul_f32 v[30:31], v[30:31], v[36:37]
	v_pk_mul_f32 v[32:33], v[32:33], v[34:35]
	v_cvt_pk_bf16_f32 v30, v30, v31
	v_cvt_pk_bf16_f32 v31, v32, v33
	v_lshl_add_u64 v[32:33], v[78:79], 1, s[36:37]
	v_lshl_add_u64 v[32:33], v[32:33], 0, v[66:67]
	global_store_dwordx2 v[32:33], v[30:31], off
	s_waitcnt vmcnt(3)
	v_lshlrev_b32_e32 v34, 16, v230
	v_and_b32_e32 v35, 0xffff0000, v230
	v_lshlrev_b32_e32 v30, 16, v231
	v_and_b32_e32 v31, 0xffff0000, v231
	v_pk_mul_f32 v[26:27], v[26:27], v[34:35]
	v_pk_mul_f32 v[28:29], v[28:29], v[30:31]
	v_cvt_pk_bf16_f32 v26, v26, v27
	v_cvt_pk_bf16_f32 v27, v28, v29
	global_store_dwordx2 v[32:33], v[26:27], off offset:32
	s_waitcnt vmcnt(3)
	v_lshlrev_b32_e32 v28, 16, v232
	v_and_b32_e32 v29, 0xffff0000, v232
	v_lshlrev_b32_e32 v26, 16, v233
	v_and_b32_e32 v27, 0xffff0000, v233
	v_pk_mul_f32 v[22:23], v[22:23], v[28:29]
	v_pk_mul_f32 v[24:25], v[24:25], v[26:27]
	v_cvt_pk_bf16_f32 v22, v22, v23
	v_cvt_pk_bf16_f32 v23, v24, v25
	global_store_dwordx2 v[32:33], v[22:23], off offset:64
	s_waitcnt vmcnt(3)
	v_lshlrev_b32_e32 v24, 16, v234
	v_and_b32_e32 v25, 0xffff0000, v234
	v_lshlrev_b32_e32 v22, 16, v235
	v_and_b32_e32 v23, 0xffff0000, v235
	v_pk_mul_f32 v[18:19], v[18:19], v[24:25]
	v_pk_mul_f32 v[20:21], v[20:21], v[22:23]
	v_cvt_pk_bf16_f32 v18, v18, v19
	v_cvt_pk_bf16_f32 v19, v20, v21
	global_store_dwordx2 v[32:33], v[18:19], off offset:96
	global_load_dwordx2 v[228:229], v[80:81], off
	global_load_dwordx2 v[230:231], v[80:81], off offset:32
	global_load_dwordx2 v[232:233], v[80:81], off offset:64
	global_load_dwordx2 v[234:235], v[80:81], off offset:96
	s_waitcnt vmcnt(3)
	v_lshlrev_b32_e32 v20, 16, v228
	v_and_b32_e32 v21, 0xffff0000, v228
	v_lshlrev_b32_e32 v18, 16, v229
	v_and_b32_e32 v19, 0xffff0000, v229
	v_pk_mul_f32 v[14:15], v[14:15], v[20:21]
	v_pk_mul_f32 v[16:17], v[16:17], v[18:19]
	v_cvt_pk_bf16_f32 v14, v14, v15
	v_cvt_pk_bf16_f32 v15, v16, v17
	v_lshl_add_u64 v[16:17], v[82:83], 1, s[36:37]
	v_lshl_add_u64 v[16:17], v[16:17], 0, v[66:67]
	global_store_dwordx2 v[16:17], v[14:15], off
	v_readlane_b32 s36, v213, 38
	s_movk_i32 s37, 0x6ff
	s_waitcnt vmcnt(3)
	v_lshlrev_b32_e32 v18, 16, v230
	v_and_b32_e32 v19, 0xffff0000, v230
	v_lshlrev_b32_e32 v14, 16, v231
	v_and_b32_e32 v15, 0xffff0000, v231
	v_pk_mul_f32 v[10:11], v[10:11], v[18:19]
	v_pk_mul_f32 v[12:13], v[12:13], v[14:15]
	v_cvt_pk_bf16_f32 v10, v10, v11
	v_cvt_pk_bf16_f32 v11, v12, v13
	global_store_dwordx2 v[16:17], v[10:11], off offset:32
	s_waitcnt vmcnt(3)
	v_lshlrev_b32_e32 v12, 16, v232
	v_and_b32_e32 v13, 0xffff0000, v232
	v_lshlrev_b32_e32 v10, 16, v233
	v_and_b32_e32 v11, 0xffff0000, v233
	v_pk_mul_f32 v[6:7], v[6:7], v[12:13]
	v_pk_mul_f32 v[8:9], v[8:9], v[10:11]
	v_cvt_pk_bf16_f32 v6, v6, v7
	v_cvt_pk_bf16_f32 v7, v8, v9
	global_store_dwordx2 v[16:17], v[6:7], off offset:64
	s_waitcnt vmcnt(3)
	v_lshlrev_b32_e32 v8, 16, v234
	v_and_b32_e32 v9, 0xffff0000, v234
	v_lshlrev_b32_e32 v6, 16, v235
	v_and_b32_e32 v7, 0xffff0000, v235
	v_pk_mul_f32 v[2:3], v[2:3], v[8:9]
	v_pk_mul_f32 v[4:5], v[4:5], v[6:7]
	v_cvt_pk_bf16_f32 v2, v2, v3
	v_cvt_pk_bf16_f32 v3, v4, v5
	global_store_dwordx2 v[16:17], v[2:3], off offset:96
	s_branch .LBB0_698

; __device__ __forceinline__ int opaque_tid() { int t = threadIdx.x; asm volatile("" : "+v"(t)); return t; }
; template <int AMODE>
; __device__ __forceinline__ void gemm_kloop(f32x4 (&acc)[4][4], const u16* __restrict__ A, int lda,
;                                            const u16* __restrict__ Bt, int ldb, int K, char* smem,
;                                            const float* __restrict__ ssq_rows) {
;     const int tid = opaque_tid(), lane = tid & 63, wid = tid >> 6, wr = wid >> 1, wc = wid & 1;
;     const int r = lane & 15, g4 = lane >> 4;
;     char* As = smem; char* Bs = smem + 32768;
;     const int grow = wid * 8 + (lane >> 3);
;     const int gch = ((lane & 7) ^ ((lane >> 3) & 7)) * 8;
;     const u16* Ag = A + (size_t)grow * lda + gch;
;     const u16* Bg = Bt + (size_t)grow * ldb + gch;
;     const int lrow = tid >> 3, lkc = tid & 7;
;     const u16* Ap = A + (size_t)lrow * lda + lkc * 8;
;     const int lds_w = lrow * 128 + ((lkc ^ (lrow & 7)) << 4);
;     uint4 ra[4];
;     float rs[4];
;     const int nk = K >> 6;
;     ...
;     GLOAD(0, 0);
;     LSTORE(0);
;     asm volatile("s_waitcnt vmcnt(0)" ::: "memory");
;     __syncthreads();
; __device__ void phaseC2(const Params& p, int l, char* smem) {
;     ...
;     for (int k = 0; k < 5; ++k) {
;         int mt, nt;
;         if (!tile_map(k, 8, mt, nt)) continue;
;         const int m0 = mt * 128, n0 = nt * 128;
;         f32x4 acc[4][4];
; #pragma unroll
;         for (int i = 0; i < 4; ++i)
; #pragma unroll
;             for (int j = 0; j < 4; ++j) acc[i][j] = (f32x4){0.f, 0.f, 0.f, 0.f};
;         gemm_kloop<0>(acc, p.ub + (size_t)m0 * 1024, 1024, p.wt_o + ((size_t)l * 1024 + n0) * 1024, 1024, 1024, smem, nullptr);
.LBB0_755:
	s_lshl_b32 s0, s11, 7
	s_ashr_i32 s1, s0, 31
	s_lshl_b32 s6, s12, 7
	s_lshl_b64 s[8:9], s[0:1], 11
	v_readlane_b32 s80, v213, 4
	v_readlane_b32 s81, v213, 5
	s_add_u32 s14, s80, s8
	s_addc_u32 s15, s81, s9
	s_ashr_i32 s7, s6, 31
	s_add_u32 s16, s6, s2
	v_mov_b32_e32 v10, v141
	s_addc_u32 s17, s7, 0
	v_readlane_b32 s36, v214, 34
	s_lshl_b64 s[16:17], s[16:17], 11
	v_ashrrev_i32_e32 v8, 6, v10
	v_bfe_u32 v0, v10, 3, 3
	v_readlane_b32 s40, v214, 38
	v_lshl_or_b32 v2, v8, 3, v0
	v_readlane_b32 s41, v214, 39
	s_add_u32 s16, s40, s16
	v_ashrrev_i32_e32 v3, 31, v2
	v_lshlrev_b32_e32 v70, 10, v8
	s_addc_u32 s17, s41, s17
	v_bitop3_b32 v0, v0, v10, 7 bitop3:0x78
	v_lshlrev_b64 v[2:3], 11, v[2:3]
	v_add_u32_e32 v8, 0x8000, v70
	v_lshlrev_b32_e32 v0, 4, v0
	v_lshl_add_u64 v[6:7], s[16:17], 0, v[2:3]
	v_readfirstlane_b32 s1, v8
	v_lshl_add_u64 v[4:5], s[14:15], 0, v[2:3]
	v_lshl_add_u64 v[6:7], v[6:7], 0, v[0:1]
	s_mov_b32 m0, s1
	v_readfirstlane_b32 s1, v70
	v_add_u32_e32 v12, 0x9000, v70
	v_lshl_add_u64 v[4:5], v[4:5], 0, v[0:1]
	global_load_lds_dwordx4 v[6:7], off
	s_mov_b32 m0, s1
	s_mov_b64 s[14:15], 0x10000
	v_readfirstlane_b32 s1, v12
	v_add_u32_e32 v12, 0x1000, v70
	global_load_lds_dwordx4 v[4:5], off
	v_lshl_add_u64 v[8:9], v[6:7], 0, s[14:15]
	s_mov_b32 m0, s1
	v_readfirstlane_b32 s1, v12
	v_add_u32_e32 v12, 0xa000, v70
	global_load_lds_dwordx4 v[8:9], off
	v_lshl_add_u64 v[8:9], v[4:5], 0, s[14:15]
	s_mov_b32 m0, s1
	s_mov_b64 s[14:15], 0x20000
	v_readfirstlane_b32 s1, v12
	v_add_u32_e32 v12, 0x2000, v70
	global_load_lds_dwordx4 v[8:9], off
	v_lshl_add_u64 v[8:9], v[6:7], 0, s[14:15]
	s_mov_b32 m0, s1
	v_readfirstlane_b32 s1, v12
	global_load_lds_dwordx4 v[8:9], off
	v_lshl_add_u64 v[8:9], v[4:5], 0, s[14:15]
	s_mov_b32 m0, s1
	s_mov_b64 s[14:15], 0x30000
	global_load_lds_dwordx4 v[8:9], off
	v_add_u32_e32 v8, 0xb000, v70
	v_lshl_add_u64 v[6:7], v[6:7], 0, s[14:15]
	v_readfirstlane_b32 s1, v8
	s_mov_b32 m0, s1
	v_lshl_add_u64 v[4:5], v[4:5], 0, s[14:15]
	global_load_lds_dwordx4 v[6:7], off
	v_add_u32_e32 v6, 0x3000, v70
	v_and_b32_e32 v11, 7, v10
	v_readfirstlane_b32 s1, v6
	s_mov_b32 m0, s1
	v_lshrrev_b32_e32 v6, 1, v10
	global_load_lds_dwordx4 v[4:5], off
	v_and_b32_e32 v5, 15, v10
	s_mov_b32 s1, 0x1ffffc0
	v_and_or_b32 v5, v6, s1, v5
	v_bfe_u32 v4, v10, 4, 2
	v_lshlrev_b32_e32 v72, 7, v5
	v_lshlrev_b32_e32 v5, 7, v10
	v_and_b32_e32 v71, 0x2780, v5
	v_bitop3_b32 v5, v4, v10, 7 bitop3:0x78
	v_bitop3_b32 v4, v4, v11, 4 bitop3:0x36
	s_lshl_b64 s[14:15], s[6:7], 11
	v_lshlrev_b32_e32 v77, 4, v5
	v_lshlrev_b32_e32 v73, 4, v4
	v_lshl_add_u64 v[4:5], s[14:15], 0, v[2:3]
	v_lshl_add_u64 v[2:3], s[8:9], 0, v[2:3]
	s_waitcnt vmcnt(0)
	v_or_b32_e32 v2, v2, v0
	v_or_b32_e32 v4, v4, v0
	v_lshl_add_u64 v[68:69], s[80:81], 0, v[2:3]
	v_mov_b32_e32 v2, 0
	v_lshl_add_u64 v[66:67], s[4:5], 0, v[4:5]
	s_mov_b64 s[8:9], 0
	s_mov_b32 s1, 0
	v_mov_b32_e32 v3, v2
	v_mov_b32_e32 v4, v2
	v_mov_b32_e32 v5, v2
	v_mov_b32_e32 v6, v2
	v_mov_b32_e32 v7, v2
	v_mov_b32_e32 v8, v2
	v_mov_b32_e32 v9, v2
	v_mov_b32_e32 v10, v2
	v_mov_b32_e32 v11, v2
	v_mov_b32_e32 v12, v2
	v_mov_b32_e32 v13, v2
	v_mov_b32_e32 v14, v2
	v_mov_b32_e32 v15, v2
	v_mov_b32_e32 v16, v2
	v_mov_b32_e32 v17, v2
	v_mov_b32_e32 v18, v2
	v_mov_b32_e32 v19, v2
	v_mov_b32_e32 v20, v2
	v_mov_b32_e32 v21, v2
	v_mov_b32_e32 v22, v2
	v_mov_b32_e32 v23, v2
	v_mov_b32_e32 v24, v2
	v_mov_b32_e32 v25, v2
	v_mov_b32_e32 v26, v2
	v_mov_b32_e32 v27, v2
	v_mov_b32_e32 v28, v2
	v_mov_b32_e32 v29, v2
	v_mov_b32_e32 v30, v2
	v_mov_b32_e32 v31, v2
	v_mov_b32_e32 v32, v2
	v_mov_b32_e32 v33, v2
	v_mov_b32_e32 v34, v2
	v_mov_b32_e32 v35, v2
	v_mov_b32_e32 v36, v2
	v_mov_b32_e32 v37, v2
	v_mov_b32_e32 v38, v2
	v_mov_b32_e32 v39, v2
	v_mov_b32_e32 v40, v2
	v_mov_b32_e32 v41, v2
	v_mov_b32_e32 v42, v2
	v_mov_b32_e32 v43, v2
	v_mov_b32_e32 v44, v2
	v_mov_b32_e32 v45, v2
	v_mov_b32_e32 v46, v2
	v_mov_b32_e32 v47, v2
	v_mov_b32_e32 v48, v2
	v_mov_b32_e32 v49, v2
	v_mov_b32_e32 v50, v2
	v_mov_b32_e32 v51, v2
	v_mov_b32_e32 v52, v2
	v_mov_b32_e32 v53, v2
	v_mov_b32_e32 v54, v2
	v_mov_b32_e32 v55, v2
	v_mov_b32_e32 v56, v2
	v_mov_b32_e32 v57, v2
	v_mov_b32_e32 v58, v2
	v_mov_b32_e32 v59, v2
	v_mov_b32_e32 v60, v2
	v_mov_b32_e32 v61, v2
	v_mov_b32_e32 v62, v2
	v_mov_b32_e32 v63, v2
	v_mov_b32_e32 v64, v2
	v_mov_b32_e32 v65, v2
	v_readlane_b32 s82, v213, 6
	v_readlane_b32 s83, v213, 7
	v_readlane_b32 s84, v213, 8
	v_readlane_b32 s85, v213, 9
	v_readlane_b32 s86, v213, 10
	v_readlane_b32 s87, v213, 11
	v_readlane_b32 s88, v213, 12
	v_readlane_b32 s89, v213, 13
	v_readlane_b32 s90, v213, 14
	v_readlane_b32 s91, v213, 15
	v_readlane_b32 s92, v213, 16
	v_readlane_b32 s93, v213, 17
	v_readlane_b32 s94, v213, 18
	v_readlane_b32 s95, v213, 19
	v_readlane_b32 s37, v214, 35
	v_readlane_b32 s38, v214, 36
	v_readlane_b32 s39, v214, 37
	v_readlane_b32 s42, v214, 40
	v_readlane_b32 s43, v214, 41
	v_readlane_b32 s44, v214, 42
	v_readlane_b32 s45, v214, 43
	v_readlane_b32 s46, v214, 44
	v_readlane_b32 s47, v214, 45
	v_readlane_b32 s48, v214, 46
	v_readlane_b32 s49, v214, 47
	v_readlane_b32 s50, v214, 48
	v_readlane_b32 s51, v214, 49
	s_waitcnt vmcnt(0) lgkmcnt(0)
	s_barrier
	v_lshrrev_b32_e32 v220, 6, v141
	v_bfe_u32 v221, v141, 3, 3
	v_lshl_or_b32 v216, v220, 3, v221
	v_and_b32_e32 v222, 7, v141
	v_xor_b32_e32 v222, v222, v221
	v_lshlrev_b32_e32 v222, 4, v222
	v_lshl_or_b32 v216, v216, 11, v222
	v_add_u32_e32 v217, 0x10000, v216
	v_add_u32_e32 v218, 0x20000, v216
	v_add_u32_e32 v219, 0x30000, v216
	v_readfirstlane_b32 s13, v220
	s_lshl_b32 s13, s13, 14
	v_readfirstlane_b32 s100, v66
	v_readfirstlane_b32 s101, v67
	s_sub_u32 s100, s100, s13
	s_subb_u32 s101, s101, 0
	v_readfirstlane_b32 s98, v68
	v_readfirstlane_b32 s99, v69
	s_sub_u32 s98, s98, s13
	s_subb_u32 s99, s99, 0
; #define MFMA(a, b, c) __builtin_amdgcn_mfma_f32_16x16x32_bf16((a), (b), (c), 0, 0, 0)
; template <int AMODE>
; __device__ __forceinline__ void gemm_kloop(f32x4 (&acc)[4][4], const u16* __restrict__ A, int lda,
;                                            const u16* __restrict__ Bt, int ldb, int K, char* smem,
;                                            const float* __restrict__ ssq_rows) {
;     ...
;     for (int kt = 0; kt < nk; ++kt) {
;         const int buf = kt & 1;
;         if (kt + 1 < nk) GLOAD(kt + 1, buf ^ 1);
;         const char* ab = As + buf * 16384 + (wr * 64 + r) * 128;
;         const char* bb = Bs + buf * 16384 + (wc * 64 + r) * 128;
;         bf16x8 af[2][4], bfr[2][4];
; #pragma unroll
;         for (int ks = 0; ks < 2; ++ks) {
;             const int co = ((ks * 4 + g4) ^ (r & 7)) << 4;
; #pragma unroll
;             for (int i = 0; i < 4; ++i) af[ks][i] = ld_frag(ab + i * 2048 + co);
; #pragma unroll
;             for (int j = 0; j < 4; ++j) bfr[ks][j] = ld_frag(bb + j * 2048 + co);
;         }
;         __builtin_amdgcn_sched_barrier(0);
;         __builtin_amdgcn_s_setprio(1);
; #pragma unroll
;         for (int ks = 0; ks < 2; ++ks)
; #pragma unroll
;             for (int i = 0; i < 4; ++i)
; #pragma unroll
;                 for (int j = 0; j < 4; ++j) acc[i][j] = MFMA(bfr[ks][j], af[ks][i], acc[i][j]);
;         __builtin_amdgcn_s_setprio(0);
;         __builtin_amdgcn_sched_barrier(0);
;         if (kt + 1 < nk) LSTORE(buf ^ 1);
;         asm volatile("s_waitcnt vmcnt(0)" ::: "memory");
;         __syncthreads();
;     }
.LBB0_756:
	s_setprio 1
	s_and_b32 s7, s1, 0x4000
	s_xor_b32 s13, s7, 0x4000
	v_add_u32_e32 v0, s13, v70
	s_add_u32 s100, s100, 0x80
	s_addc_u32 s101, s101, 0
	s_add_u32 s98, s98, 0x80
	s_addc_u32 s99, s99, 0
	v_readfirstlane_b32 s13, v0
	s_add_u32 m0, s13, 0x8000
	v_or_b32_e32 v102, s7, v71
	global_load_lds_dwordx4 v216, s[100:101]
	v_add_u32_e32 v0, s7, v72
	s_add_u32 m0, s13, 0x0
	v_add_u32_e32 v90, v0, v77
	global_load_lds_dwordx4 v216, s[98:99]
	v_add_u32_e32 v103, v102, v77
	s_add_u32 m0, s13, 0x9000
	v_add_u32_e32 v0, v0, v73
	global_load_lds_dwordx4 v217, s[100:101]
	ds_read_b128 v[78:81], v90
	s_add_u32 m0, s13, 0x1000
	ds_read_b128 v[82:85], v90 offset:2048
	global_load_lds_dwordx4 v217, s[98:99]
	ds_read_b128 v[86:89], v90 offset:4096
	s_add_u32 m0, s13, 0xa000
	ds_read_b128 v[90:93], v90 offset:6144
	global_load_lds_dwordx4 v218, s[100:101]
	ds_read_b128 v[94:97], v103 offset:32768
	s_add_u32 m0, s13, 0x2000
	ds_read_b128 v[98:101], v103 offset:34816
	global_load_lds_dwordx4 v218, s[98:99]
	ds_read_b128 v[110:113], v103 offset:36864
	s_add_u32 m0, s13, 0xb000
	ds_read_b128 v[114:117], v103 offset:38912
	global_load_lds_dwordx4 v219, s[100:101]
	ds_read_b128 v[118:121], v0
	s_add_u32 m0, s13, 0x3000
	ds_read_b128 v[122:125], v0 offset:2048
	global_load_lds_dwordx4 v219, s[98:99]
	ds_read_b128 v[126:129], v0 offset:4096
	ds_read_b128 v[130:133], v0 offset:6144
	v_add_u32_e32 v0, v102, v73
	ds_read_b128 v[134:137], v0 offset:32768
	ds_read_b128 v[142:145], v0 offset:34816
	ds_read_b128 v[146:149], v0 offset:36864
	ds_read_b128 v[150:153], v0 offset:38912
	s_setprio 0
	s_waitcnt lgkmcnt(0)
	v_mfma_f32_16x16x32_bf16 v[62:65], v[94:97], v[78:81], v[62:65]
	v_mfma_f32_16x16x32_bf16 v[58:61], v[98:101], v[78:81], v[58:61]
	v_mfma_f32_16x16x32_bf16 v[54:57], v[110:113], v[78:81], v[54:57]
	v_mfma_f32_16x16x32_bf16 v[50:53], v[114:117], v[78:81], v[50:53]
	v_mfma_f32_16x16x32_bf16 v[46:49], v[94:97], v[82:85], v[46:49]
	v_mfma_f32_16x16x32_bf16 v[42:45], v[98:101], v[82:85], v[42:45]
	v_mfma_f32_16x16x32_bf16 v[38:41], v[110:113], v[82:85], v[38:41]
	v_mfma_f32_16x16x32_bf16 v[34:37], v[114:117], v[82:85], v[34:37]
	v_mfma_f32_16x16x32_bf16 v[30:33], v[94:97], v[86:89], v[30:33]
	v_mfma_f32_16x16x32_bf16 v[26:29], v[98:101], v[86:89], v[26:29]
	v_mfma_f32_16x16x32_bf16 v[22:25], v[110:113], v[86:89], v[22:25]
	v_mfma_f32_16x16x32_bf16 v[18:21], v[114:117], v[86:89], v[18:21]
	v_mfma_f32_16x16x32_bf16 v[14:17], v[94:97], v[90:93], v[14:17]
	v_mfma_f32_16x16x32_bf16 v[10:13], v[98:101], v[90:93], v[10:13]
	v_mfma_f32_16x16x32_bf16 v[6:9], v[110:113], v[90:93], v[6:9]
	v_mfma_f32_16x16x32_bf16 v[2:5], v[114:117], v[90:93], v[2:5]
	v_mfma_f32_16x16x32_bf16 v[62:65], v[134:137], v[118:121], v[62:65]
	v_mfma_f32_16x16x32_bf16 v[58:61], v[142:145], v[118:121], v[58:61]
	v_mfma_f32_16x16x32_bf16 v[54:57], v[146:149], v[118:121], v[54:57]
	v_mfma_f32_16x16x32_bf16 v[50:53], v[150:153], v[118:121], v[50:53]
	v_mfma_f32_16x16x32_bf16 v[46:49], v[134:137], v[122:125], v[46:49]
	v_mfma_f32_16x16x32_bf16 v[42:45], v[142:145], v[122:125], v[42:45]
	v_mfma_f32_16x16x32_bf16 v[38:41], v[146:149], v[122:125], v[38:41]
	v_mfma_f32_16x16x32_bf16 v[34:37], v[150:153], v[122:125], v[34:37]
	v_mfma_f32_16x16x32_bf16 v[30:33], v[134:137], v[126:129], v[30:33]
	v_mfma_f32_16x16x32_bf16 v[26:29], v[142:145], v[126:129], v[26:29]
	v_mfma_f32_16x16x32_bf16 v[22:25], v[146:149], v[126:129], v[22:25]
	v_mfma_f32_16x16x32_bf16 v[18:21], v[150:153], v[126:129], v[18:21]
	v_mfma_f32_16x16x32_bf16 v[14:17], v[134:137], v[130:133], v[14:17]
	v_mfma_f32_16x16x32_bf16 v[10:13], v[142:145], v[130:133], v[10:13]
	v_mfma_f32_16x16x32_bf16 v[6:9], v[146:149], v[130:133], v[6:9]
	v_mfma_f32_16x16x32_bf16 v[2:5], v[150:153], v[130:133], v[2:5]
	s_nop 0
	s_waitcnt vmcnt(0)
	s_add_u32 s8, s8, 0x80
	s_addc_u32 s9, s9, 0
	s_addk_i32 s1, 0x4000
	s_cmpk_eq_i32 s8, 0x780
	s_waitcnt vmcnt(0)
	s_barrier
	s_cbranch_scc0 .LBB0_756
; #define MFMA(a, b, c) __builtin_amdgcn_mfma_f32_16x16x32_bf16((a), (b), (c), 0, 0, 0)
; template <int AMODE>
; __device__ __forceinline__ void gemm_kloop(f32x4 (&acc)[4][4], const u16* __restrict__ A, int lda,
;                                            const u16* __restrict__ Bt, int ldb, int K, char* smem,
;                                            const float* __restrict__ ssq_rows) {
;     ...
;         for (int ks = 0; ks < 2; ++ks)
; #pragma unroll
;             for (int i = 0; i < 4; ++i)
; #pragma unroll
;                 for (int j = 0; j < 4; ++j) acc[i][j] = MFMA(bfr[ks][j], af[ks][i], acc[i][j]);
; __device__ void phaseC2(const Params& p, int l, char* smem) {
;     ...
; #pragma unroll
;         for (int i = 0; i < 4; ++i) {
;             const size_t row = (size_t)(m0 + wr * 64 + i * 16 + r);
;             const float* xr;
;             if (l == 0) xr = (row < TP) ? (p.x_prompt + row * 1024) : (p.x_sample + (row - TP) * 1024);
;             else xr = p.out + O_Y + row * 1024;
	v_add_u32_e32 v0, v72, v77
	ds_read_b128 v[66:69], v0 offset:16384
	ds_read_b128 v[78:81], v0 offset:18432
	ds_read_b128 v[82:85], v0 offset:20480
	ds_read_b128 v[86:89], v0 offset:22528
	v_add_u32_e32 v0, v71, v77
	ds_read_b128 v[90:93], v0 offset:49152
	ds_read_b128 v[94:97], v0 offset:51200
	ds_read_b128 v[98:101], v0 offset:53248
	ds_read_b128 v[110:113], v0 offset:55296
	v_add_u32_e32 v0, v72, v73
	ds_read_b128 v[114:117], v0 offset:16384
	ds_read_b128 v[118:121], v0 offset:18432
	ds_read_b128 v[122:125], v0 offset:20480
	ds_read_b128 v[126:129], v0 offset:22528
	v_add_u32_e32 v0, v71, v73
	ds_read_b128 v[70:73], v0 offset:49152
	ds_read_b128 v[130:133], v0 offset:51200
	ds_read_b128 v[134:137], v0 offset:53248
	ds_read_b128 v[142:145], v0 offset:55296
	s_setprio 1
	s_waitcnt lgkmcnt(11)
	v_mfma_f32_16x16x32_bf16 v[62:65], v[90:93], v[66:69], v[62:65]
	s_waitcnt lgkmcnt(10)
	v_mfma_f32_16x16x32_bf16 v[58:61], v[94:97], v[66:69], v[58:61]
	s_waitcnt lgkmcnt(9)
	v_mfma_f32_16x16x32_bf16 v[54:57], v[98:101], v[66:69], v[54:57]
	s_waitcnt lgkmcnt(8)
	v_mfma_f32_16x16x32_bf16 v[50:53], v[110:113], v[66:69], v[50:53]
	v_mfma_f32_16x16x32_bf16 v[46:49], v[90:93], v[78:81], v[46:49]
	v_mfma_f32_16x16x32_bf16 v[42:45], v[94:97], v[78:81], v[42:45]
	v_mfma_f32_16x16x32_bf16 v[38:41], v[98:101], v[78:81], v[38:41]
	v_mfma_f32_16x16x32_bf16 v[34:37], v[110:113], v[78:81], v[34:37]
	v_mfma_f32_16x16x32_bf16 v[30:33], v[90:93], v[82:85], v[30:33]
	v_mfma_f32_16x16x32_bf16 v[26:29], v[94:97], v[82:85], v[26:29]
	v_mfma_f32_16x16x32_bf16 v[22:25], v[98:101], v[82:85], v[22:25]
	v_mfma_f32_16x16x32_bf16 v[18:21], v[110:113], v[82:85], v[18:21]
	v_mfma_f32_16x16x32_bf16 v[14:17], v[90:93], v[86:89], v[14:17]
	v_mfma_f32_16x16x32_bf16 v[10:13], v[94:97], v[86:89], v[10:13]
	v_mfma_f32_16x16x32_bf16 v[6:9], v[98:101], v[86:89], v[6:9]
	v_mfma_f32_16x16x32_bf16 v[2:5], v[110:113], v[86:89], v[2:5]
	s_waitcnt lgkmcnt(3)
	v_mfma_f32_16x16x32_bf16 v[62:65], v[70:73], v[114:117], v[62:65]
	s_waitcnt lgkmcnt(2)
	v_mfma_f32_16x16x32_bf16 v[58:61], v[130:133], v[114:117], v[58:61]
	s_waitcnt lgkmcnt(1)
	v_mfma_f32_16x16x32_bf16 v[54:57], v[134:137], v[114:117], v[54:57]
	s_waitcnt lgkmcnt(0)
	v_mfma_f32_16x16x32_bf16 v[50:53], v[142:145], v[114:117], v[50:53]
	v_mfma_f32_16x16x32_bf16 v[46:49], v[70:73], v[118:121], v[46:49]
	v_mfma_f32_16x16x32_bf16 v[42:45], v[130:133], v[118:121], v[42:45]
	v_mfma_f32_16x16x32_bf16 v[38:41], v[134:137], v[118:121], v[38:41]
	v_mfma_f32_16x16x32_bf16 v[34:37], v[142:145], v[118:121], v[34:37]
	v_mfma_f32_16x16x32_bf16 v[30:33], v[70:73], v[122:125], v[30:33]
	v_mfma_f32_16x16x32_bf16 v[26:29], v[130:133], v[122:125], v[26:29]
	v_mfma_f32_16x16x32_bf16 v[22:25], v[134:137], v[122:125], v[22:25]
	v_mfma_f32_16x16x32_bf16 v[18:21], v[142:145], v[122:125], v[18:21]
	v_mfma_f32_16x16x32_bf16 v[14:17], v[70:73], v[126:129], v[14:17]
	v_mfma_f32_16x16x32_bf16 v[10:13], v[130:133], v[126:129], v[10:13]
	v_mfma_f32_16x16x32_bf16 v[6:9], v[134:137], v[126:129], v[6:9]
	v_mfma_f32_16x16x32_bf16 v[2:5], v[142:145], v[126:129], v[2:5]
	s_setprio 0
	v_add_u32_e32 v0, s0, v75
	s_waitcnt vmcnt(0)
	v_or_b32_e32 v66, v0, v74
	v_ashrrev_i32_e32 v67, 31, v66
	v_readlane_b32 s80, v213, 44
	v_lshlrev_b64 v[70:71], 12, v[66:67]
	s_mov_b64 s[0:1], -1
	s_and_b64 vcc, exec, s[74:75]
	v_readlane_b32 s81, v213, 45
	v_readlane_b32 s82, v213, 46
	v_readlane_b32 s83, v213, 47
	v_readlane_b32 s84, v213, 48
	v_readlane_b32 s85, v213, 49
	v_readlane_b32 s86, v213, 50
	v_readlane_b32 s87, v213, 51
	v_readlane_b32 s88, v213, 52
	v_readlane_b32 s89, v213, 53
	v_readlane_b32 s90, v213, 54
	v_readlane_b32 s91, v213, 55
	v_readlane_b32 s92, v213, 56
	v_readlane_b32 s93, v213, 57
	s_barrier
	v_readlane_b32 s94, v213, 58
	v_readlane_b32 s95, v213, 59
	s_cbranch_vccz .LBB0_759
	v_readlane_b32 s16, v214, 0
	v_readlane_b32 s26, v214, 10
	v_readlane_b32 s27, v214, 11
	v_readlane_b32 s17, v214, 1
	v_readlane_b32 s18, v214, 2
	v_readlane_b32 s19, v214, 3
	v_readlane_b32 s20, v214, 4
	v_readlane_b32 s21, v214, 5
	v_readlane_b32 s22, v214, 6
	v_readlane_b32 s23, v214, 7
	v_readlane_b32 s24, v214, 8
	v_readlane_b32 s25, v214, 9
	v_readlane_b32 s28, v214, 12
	v_readlane_b32 s29, v214, 13
	v_readlane_b32 s30, v214, 14
	v_readlane_b32 s31, v214, 15
	v_lshl_add_u64 v[72:73], s[26:27], 0, v[70:71]
	s_mov_b64 s[0:1], 0
